# A/B: per-phase s_setprio flips removed from the stream GEMM K loops, static raise for waves 4-7 only
# speedup vs baseline: 1.0074x; 1.0007x over previous
.LBB0_32:
	s_add_i32 s11, s10, 2
	ds_read_b128 v[132:135], v159
	ds_read_b128 v[136:139], v160
	ds_read_b128 v[180:183], v161
	ds_read_b128 v[184:187], v162
	s_cmpk_lt_u32 s10, 0x56
	s_cselect_b32 s12, s8, s5
	s_cselect_b32 s13, s7, s6
	s_cselect_b32 s14, s9, 0
	s_mulk_i32 s13, 0x1600
	s_mulk_i32 s12, 0x1600
	s_or_b32 s15, s14, 64
	s_add_i32 s17, s12, s14
	s_add_i32 s18, s13, 0xb0000
	s_add_i32 s16, s13, s14
	s_add_i32 s13, s15, s13
	s_add_i32 s12, s15, s12
	s_lshl_b32 s17, s17, 1
	s_add_i32 s14, s18, s14
	s_add_i32 s18, s18, s15
	s_addk_i32 s9, 0x80
	s_lshl_b32 s16, s16, 1
	s_lshl_b32 s19, s13, 1
	s_lshl_b32 s13, s12, 1
	s_lshl_b32 s14, s14, 1
	s_add_i32 s15, s17, 0x160000
	s_lshl_b32 s12, s18, 1
	s_cmpk_gt_u32 s10, 0x55
	v_readfirstlane_b32 s10, v163
	v_add_u32_e32 v131, 0xfff50000, v130
	s_mov_b32 m0, s10
	v_readfirstlane_b32 s10, v165
	ds_read_b128 v[188:191], v157
	ds_read_b128 v[192:195], v157 offset:1024
	ds_read_b128 v[196:199], v157 offset:2048
	ds_read_b128 v[200:203], v157 offset:3072
	ds_read_b128 v[204:207], v157 offset:4096
	ds_read_b128 v[208:211], v157 offset:5120
	ds_read_b128 v[212:215], v157 offset:6144
	ds_read_b128 v[216:219], v157 offset:7168
	global_load_lds_dwordx4 v131, s[76:77]
	s_mov_b32 m0, s10
	s_nop 0
	global_load_lds_dwordx4 v130, s[76:77]
	s_waitcnt lgkmcnt(8)
	ds_read_b128 v[220:223], v166
	ds_read_b128 v[242:245], v167
	ds_read_b128 v[246:249], v168
	ds_read_b128 v[250:253], v169
	s_waitcnt vmcnt(8)
	s_waitcnt lgkmcnt(0)
	s_barrier
	v_mfma_f32_16x16x32_bf16 v[126:129], v[132:135], v[188:191], v[126:129]
	v_mfma_f32_16x16x32_bf16 v[122:125], v[180:183], v[188:191], v[122:125]
	v_mfma_f32_16x16x32_bf16 v[118:121], v[132:135], v[196:199], v[118:121]
	v_mfma_f32_16x16x32_bf16 v[114:117], v[180:183], v[196:199], v[114:117]
	v_mfma_f32_16x16x32_bf16 v[110:113], v[132:135], v[204:207], v[110:113]
	v_mfma_f32_16x16x32_bf16 v[106:109], v[180:183], v[204:207], v[106:109]
	v_mfma_f32_16x16x32_bf16 v[102:105], v[132:135], v[212:215], v[102:105]
	v_mfma_f32_16x16x32_bf16 v[98:101], v[180:183], v[212:215], v[98:101]
	v_mfma_f32_16x16x32_bf16 v[126:129], v[136:139], v[192:195], v[126:129]
	v_mfma_f32_16x16x32_bf16 v[122:125], v[184:187], v[192:195], v[122:125]
	v_mfma_f32_16x16x32_bf16 v[118:121], v[136:139], v[200:203], v[118:121]
	v_mfma_f32_16x16x32_bf16 v[114:117], v[184:187], v[200:203], v[114:117]
	v_mfma_f32_16x16x32_bf16 v[110:113], v[136:139], v[208:211], v[110:113]
	v_mfma_f32_16x16x32_bf16 v[106:109], v[184:187], v[208:211], v[106:109]
	v_mfma_f32_16x16x32_bf16 v[102:105], v[136:139], v[216:219], v[102:105]
	v_mfma_f32_16x16x32_bf16 v[98:101], v[184:187], v[216:219], v[98:101]
	v_mfma_f32_16x16x32_bf16 v[94:97], v[220:223], v[188:191], v[94:97]
	v_mfma_f32_16x16x32_bf16 v[90:93], v[246:249], v[188:191], v[90:93]
	v_mfma_f32_16x16x32_bf16 v[86:89], v[220:223], v[196:199], v[86:89]
	v_mfma_f32_16x16x32_bf16 v[82:85], v[246:249], v[196:199], v[82:85]
	v_mfma_f32_16x16x32_bf16 v[78:81], v[220:223], v[204:207], v[78:81]
	v_mfma_f32_16x16x32_bf16 v[74:77], v[246:249], v[204:207], v[74:77]
	v_mfma_f32_16x16x32_bf16 v[70:73], v[220:223], v[212:215], v[70:73]
	v_mfma_f32_16x16x32_bf16 v[66:69], v[246:249], v[212:215], v[66:69]
	v_mfma_f32_16x16x32_bf16 v[94:97], v[242:245], v[192:195], v[94:97]
	v_mfma_f32_16x16x32_bf16 v[90:93], v[250:253], v[192:195], v[90:93]
	v_mfma_f32_16x16x32_bf16 v[86:89], v[242:245], v[200:203], v[86:89]
	v_mfma_f32_16x16x32_bf16 v[82:85], v[250:253], v[200:203], v[82:85]
	v_mfma_f32_16x16x32_bf16 v[78:81], v[242:245], v[208:211], v[78:81]
	v_mfma_f32_16x16x32_bf16 v[74:77], v[250:253], v[208:211], v[74:77]
	v_mfma_f32_16x16x32_bf16 v[70:73], v[242:245], v[216:219], v[70:73]
	v_mfma_f32_16x16x32_bf16 v[66:69], v[250:253], v[216:219], v[66:69]
	s_barrier
	v_readfirstlane_b32 s10, v144
	v_add_u32_e32 v131, s16, v142
	s_mov_b32 m0, s10
	v_readfirstlane_b32 s10, v145
	global_load_lds_dwordx4 v131, s[78:79]
	v_add_u32_e32 v131, s16, v143
	s_mov_b32 m0, s10
	s_nop 0
	global_load_lds_dwordx4 v131, s[78:79]
	v_readfirstlane_b32 s10, v0
	v_add_u32_e32 v131, s17, v142
	s_mov_b32 m0, s10
	v_readfirstlane_b32 s10, v146
	ds_read_b128 v[188:191], v157 offset:16384
	ds_read_b128 v[192:195], v157 offset:17408
	ds_read_b128 v[196:199], v157 offset:18432
	ds_read_b128 v[200:203], v157 offset:19456
	ds_read_b128 v[204:207], v157 offset:20480
	ds_read_b128 v[208:211], v157 offset:21504
	ds_read_b128 v[212:215], v157 offset:22528
	ds_read_b128 v[216:219], v157 offset:23552
	global_load_lds_dwordx4 v131, s[76:77]
	v_add_u32_e32 v131, s17, v143
	s_mov_b32 m0, s10
	s_nop 0
	global_load_lds_dwordx4 v131, s[76:77]
	v_readfirstlane_b32 s10, v147
	v_add_u32_e32 v131, s14, v142
	s_mov_b32 m0, s10
	v_readfirstlane_b32 s10, v148
	global_load_lds_dwordx4 v131, s[78:79]
	v_add_u32_e32 v131, s14, v143
	s_mov_b32 m0, s10
	s_nop 0
	global_load_lds_dwordx4 v131, s[78:79]
	s_waitcnt vmcnt(8)
	s_waitcnt lgkmcnt(0)
	s_barrier
	v_mfma_f32_16x16x32_bf16 v[62:65], v[132:135], v[188:191], v[62:65]
	v_mfma_f32_16x16x32_bf16 v[58:61], v[180:183], v[188:191], v[58:61]
	v_mfma_f32_16x16x32_bf16 v[54:57], v[132:135], v[196:199], v[54:57]
	v_mfma_f32_16x16x32_bf16 v[50:53], v[180:183], v[196:199], v[50:53]
	v_mfma_f32_16x16x32_bf16 v[46:49], v[132:135], v[204:207], v[46:49]
	v_mfma_f32_16x16x32_bf16 v[42:45], v[180:183], v[204:207], v[42:45]
	v_mfma_f32_16x16x32_bf16 v[38:41], v[132:135], v[212:215], v[38:41]
	v_mfma_f32_16x16x32_bf16 v[34:37], v[180:183], v[212:215], v[34:37]
	v_mfma_f32_16x16x32_bf16 v[62:65], v[136:139], v[192:195], v[62:65]
	v_mfma_f32_16x16x32_bf16 v[58:61], v[184:187], v[192:195], v[58:61]
	v_mfma_f32_16x16x32_bf16 v[54:57], v[136:139], v[200:203], v[54:57]
	v_mfma_f32_16x16x32_bf16 v[50:53], v[184:187], v[200:203], v[50:53]
	v_mfma_f32_16x16x32_bf16 v[46:49], v[136:139], v[208:211], v[46:49]
	v_mfma_f32_16x16x32_bf16 v[42:45], v[184:187], v[208:211], v[42:45]
	v_mfma_f32_16x16x32_bf16 v[38:41], v[136:139], v[216:219], v[38:41]
	v_mfma_f32_16x16x32_bf16 v[34:37], v[184:187], v[216:219], v[34:37]
	v_mfma_f32_16x16x32_bf16 v[30:33], v[220:223], v[188:191], v[30:33]
	v_mfma_f32_16x16x32_bf16 v[26:29], v[246:249], v[188:191], v[26:29]
	v_mfma_f32_16x16x32_bf16 v[22:25], v[220:223], v[196:199], v[22:25]
	v_mfma_f32_16x16x32_bf16 v[18:21], v[246:249], v[196:199], v[18:21]
	v_mfma_f32_16x16x32_bf16 v[14:17], v[220:223], v[204:207], v[14:17]
	v_mfma_f32_16x16x32_bf16 v[10:13], v[246:249], v[204:207], v[10:13]
	v_mfma_f32_16x16x32_bf16 v[6:9], v[220:223], v[212:215], v[6:9]
	v_mfma_f32_16x16x32_bf16 v[2:5], v[246:249], v[212:215], v[2:5]
	v_mfma_f32_16x16x32_bf16 v[30:33], v[242:245], v[192:195], v[30:33]
	v_mfma_f32_16x16x32_bf16 v[26:29], v[250:253], v[192:195], v[26:29]
	v_mfma_f32_16x16x32_bf16 v[22:25], v[242:245], v[200:203], v[22:25]
	v_mfma_f32_16x16x32_bf16 v[18:21], v[250:253], v[200:203], v[18:21]
	v_mfma_f32_16x16x32_bf16 v[14:17], v[242:245], v[208:211], v[14:17]
	v_mfma_f32_16x16x32_bf16 v[10:13], v[250:253], v[208:211], v[10:13]
	v_mfma_f32_16x16x32_bf16 v[6:9], v[242:245], v[216:219], v[6:9]
	v_mfma_f32_16x16x32_bf16 v[2:5], v[250:253], v[216:219], v[2:5]
	s_barrier
	ds_read_b128 v[132:135], v170
	ds_read_b128 v[136:139], v171
	ds_read_b128 v[180:183], v172
	ds_read_b128 v[184:187], v173
	v_readfirstlane_b32 s10, v149
	v_add_u32_e32 v131, s15, v142
	s_mov_b32 m0, s10
	v_readfirstlane_b32 s10, v150
	ds_read_b128 v[188:191], v157 offset:32768
	ds_read_b128 v[192:195], v157 offset:33792
	ds_read_b128 v[196:199], v157 offset:34816
	ds_read_b128 v[200:203], v157 offset:35840
	ds_read_b128 v[204:207], v157 offset:36864
	ds_read_b128 v[208:211], v157 offset:37888
	ds_read_b128 v[212:215], v157 offset:38912
	ds_read_b128 v[216:219], v157 offset:39936
	global_load_lds_dwordx4 v131, s[76:77]
	v_add_u32_e32 v131, s15, v143
	s_mov_b32 m0, s10
	s_nop 0
	global_load_lds_dwordx4 v131, s[76:77]
	s_waitcnt lgkmcnt(8)
	ds_read_b128 v[220:223], v174
	ds_read_b128 v[242:245], v175
	ds_read_b128 v[246:249], v176
	ds_read_b128 v[250:253], v177
	s_waitcnt vmcnt(8)
	s_waitcnt lgkmcnt(0)
	s_barrier
	v_mfma_f32_16x16x32_bf16 v[126:129], v[132:135], v[188:191], v[126:129]
	v_mfma_f32_16x16x32_bf16 v[122:125], v[180:183], v[188:191], v[122:125]
	v_mfma_f32_16x16x32_bf16 v[118:121], v[132:135], v[196:199], v[118:121]
	v_mfma_f32_16x16x32_bf16 v[114:117], v[180:183], v[196:199], v[114:117]
	v_mfma_f32_16x16x32_bf16 v[110:113], v[132:135], v[204:207], v[110:113]
	v_mfma_f32_16x16x32_bf16 v[106:109], v[180:183], v[204:207], v[106:109]
	v_mfma_f32_16x16x32_bf16 v[102:105], v[132:135], v[212:215], v[102:105]
	v_mfma_f32_16x16x32_bf16 v[98:101], v[180:183], v[212:215], v[98:101]
	v_mfma_f32_16x16x32_bf16 v[126:129], v[136:139], v[192:195], v[126:129]
	v_mfma_f32_16x16x32_bf16 v[122:125], v[184:187], v[192:195], v[122:125]
	v_mfma_f32_16x16x32_bf16 v[118:121], v[136:139], v[200:203], v[118:121]
	v_mfma_f32_16x16x32_bf16 v[114:117], v[184:187], v[200:203], v[114:117]
	v_mfma_f32_16x16x32_bf16 v[110:113], v[136:139], v[208:211], v[110:113]
	v_mfma_f32_16x16x32_bf16 v[106:109], v[184:187], v[208:211], v[106:109]
	v_mfma_f32_16x16x32_bf16 v[102:105], v[136:139], v[216:219], v[102:105]
	v_mfma_f32_16x16x32_bf16 v[98:101], v[184:187], v[216:219], v[98:101]
	v_mfma_f32_16x16x32_bf16 v[94:97], v[220:223], v[188:191], v[94:97]
	v_mfma_f32_16x16x32_bf16 v[90:93], v[246:249], v[188:191], v[90:93]
	v_mfma_f32_16x16x32_bf16 v[86:89], v[220:223], v[196:199], v[86:89]
	v_mfma_f32_16x16x32_bf16 v[82:85], v[246:249], v[196:199], v[82:85]
	v_mfma_f32_16x16x32_bf16 v[78:81], v[220:223], v[204:207], v[78:81]
	v_mfma_f32_16x16x32_bf16 v[74:77], v[246:249], v[204:207], v[74:77]
	v_mfma_f32_16x16x32_bf16 v[70:73], v[220:223], v[212:215], v[70:73]
	v_mfma_f32_16x16x32_bf16 v[66:69], v[246:249], v[212:215], v[66:69]
	v_mfma_f32_16x16x32_bf16 v[94:97], v[242:245], v[192:195], v[94:97]
	v_mfma_f32_16x16x32_bf16 v[90:93], v[250:253], v[192:195], v[90:93]
	v_mfma_f32_16x16x32_bf16 v[86:89], v[242:245], v[200:203], v[86:89]
	v_mfma_f32_16x16x32_bf16 v[82:85], v[250:253], v[200:203], v[82:85]
	v_mfma_f32_16x16x32_bf16 v[78:81], v[242:245], v[208:211], v[78:81]
	v_mfma_f32_16x16x32_bf16 v[74:77], v[250:253], v[208:211], v[74:77]
	v_mfma_f32_16x16x32_bf16 v[70:73], v[242:245], v[216:219], v[70:73]
	v_mfma_f32_16x16x32_bf16 v[66:69], v[250:253], v[216:219], v[66:69]
	s_barrier
; DI void gemm_resid(const u16* A, const u16* Bt, int K, const float* xin, float* xout, int bid, int nb, int tid) {
;     ...
;     for (int ai = 0; ai < 2; ++ai)
; #pragma unroll
;       for (int bj = 0; bj < 2; ++bj) {
;         float4 xi[4][2];
; #pragma unroll
;         for (int m = 0; m < 4; ++m)
; #pragma unroll
;           for (int n = 0; n < 2; ++n) xi[m][n] = *reinterpret_cast<const float4*>(xin + (size_t)ACC_ROW * 2048 + ACC_COL);
	v_readfirstlane_b32 s10, v151
	v_add_u32_e32 v131, s19, v142
	s_mov_b32 m0, s10
	v_readfirstlane_b32 s10, v152
	global_load_lds_dwordx4 v131, s[78:79]
	v_add_u32_e32 v131, s19, v143
	s_mov_b32 m0, s10
	s_nop 0
	global_load_lds_dwordx4 v131, s[78:79]
	v_readfirstlane_b32 s10, v153
	v_add_u32_e32 v131, s13, v142
	s_mov_b32 m0, s10
	v_readfirstlane_b32 s10, v154
	ds_read_b128 v[188:191], v157 offset:49152
	ds_read_b128 v[192:195], v157 offset:50176
	ds_read_b128 v[196:199], v157 offset:51200
	ds_read_b128 v[200:203], v157 offset:52224
	ds_read_b128 v[204:207], v157 offset:53248
	ds_read_b128 v[208:211], v157 offset:54272
	ds_read_b128 v[212:215], v157 offset:55296
	ds_read_b128 v[216:219], v157 offset:56320
	global_load_lds_dwordx4 v131, s[76:77]
	v_add_u32_e32 v131, s13, v143
	s_mov_b32 m0, s10
	s_nop 0
	global_load_lds_dwordx4 v131, s[76:77]
	v_readfirstlane_b32 s10, v155
	v_add_u32_e32 v131, s12, v142
	s_mov_b32 m0, s10
	v_readfirstlane_b32 s10, v156
	global_load_lds_dwordx4 v131, s[78:79]
	v_add_u32_e32 v131, s12, v143
	s_mov_b32 m0, s10
	s_nop 0
	global_load_lds_dwordx4 v131, s[78:79]
	s_waitcnt vmcnt(8)
	s_waitcnt lgkmcnt(0)
	s_barrier
	v_mfma_f32_16x16x32_bf16 v[62:65], v[132:135], v[188:191], v[62:65]
	v_mfma_f32_16x16x32_bf16 v[58:61], v[180:183], v[188:191], v[58:61]
	v_mfma_f32_16x16x32_bf16 v[54:57], v[132:135], v[196:199], v[54:57]
	v_mfma_f32_16x16x32_bf16 v[50:53], v[180:183], v[196:199], v[50:53]
	v_mfma_f32_16x16x32_bf16 v[46:49], v[132:135], v[204:207], v[46:49]
	v_mfma_f32_16x16x32_bf16 v[42:45], v[180:183], v[204:207], v[42:45]
	v_mfma_f32_16x16x32_bf16 v[38:41], v[132:135], v[212:215], v[38:41]
	v_mfma_f32_16x16x32_bf16 v[34:37], v[180:183], v[212:215], v[34:37]
	v_mfma_f32_16x16x32_bf16 v[62:65], v[136:139], v[192:195], v[62:65]
	v_mfma_f32_16x16x32_bf16 v[58:61], v[184:187], v[192:195], v[58:61]
	v_mfma_f32_16x16x32_bf16 v[54:57], v[136:139], v[200:203], v[54:57]
	v_mfma_f32_16x16x32_bf16 v[50:53], v[184:187], v[200:203], v[50:53]
	v_mfma_f32_16x16x32_bf16 v[46:49], v[136:139], v[208:211], v[46:49]
	v_mfma_f32_16x16x32_bf16 v[42:45], v[184:187], v[208:211], v[42:45]
	v_mfma_f32_16x16x32_bf16 v[38:41], v[136:139], v[216:219], v[38:41]
	v_mfma_f32_16x16x32_bf16 v[34:37], v[184:187], v[216:219], v[34:37]
	v_mfma_f32_16x16x32_bf16 v[30:33], v[220:223], v[188:191], v[30:33]
	v_mfma_f32_16x16x32_bf16 v[26:29], v[246:249], v[188:191], v[26:29]
	v_mfma_f32_16x16x32_bf16 v[22:25], v[220:223], v[196:199], v[22:25]
	v_mfma_f32_16x16x32_bf16 v[18:21], v[246:249], v[196:199], v[18:21]
	v_mfma_f32_16x16x32_bf16 v[14:17], v[220:223], v[204:207], v[14:17]
	v_mfma_f32_16x16x32_bf16 v[10:13], v[246:249], v[204:207], v[10:13]
	v_mfma_f32_16x16x32_bf16 v[6:9], v[220:223], v[212:215], v[6:9]
	v_mfma_f32_16x16x32_bf16 v[2:5], v[246:249], v[212:215], v[2:5]
	v_mfma_f32_16x16x32_bf16 v[30:33], v[242:245], v[192:195], v[30:33]
	v_mfma_f32_16x16x32_bf16 v[26:29], v[250:253], v[192:195], v[26:29]
	v_mfma_f32_16x16x32_bf16 v[22:25], v[242:245], v[200:203], v[22:25]
	v_mfma_f32_16x16x32_bf16 v[18:21], v[250:253], v[200:203], v[18:21]
	v_mfma_f32_16x16x32_bf16 v[14:17], v[242:245], v[208:211], v[14:17]
	v_mfma_f32_16x16x32_bf16 v[10:13], v[250:253], v[208:211], v[10:13]
	v_mfma_f32_16x16x32_bf16 v[6:9], v[242:245], v[216:219], v[6:9]
	v_mfma_f32_16x16x32_bf16 v[2:5], v[250:253], v[216:219], v[2:5]
	v_add_u32_e32 v130, 0x100, v130
	s_mov_b32 s10, s11
	s_barrier
	s_cbranch_scc0 .LBB0_32
	v_mov_b32_e32 v131, v239
	s_nop 0
	v_ashrrev_i32_e32 v130, 2, v131
	v_and_b32_e32 v130, 0xffffffc0, v130
	v_and_or_b32 v132, v131, 15, s8
	v_add_u32_e32 v130, v132, v130
	v_lshrrev_b32_e32 v132, 1, v131
	v_lshrrev_b32_e32 v131, 2, v131
	v_and_b32_e32 v132, 0x60, v132
	v_and_b32_e32 v131, 12, v131
	v_or3_b32 v132, v132, v131, s7
	v_ashrrev_i32_e32 v131, 31, v130
	v_ashrrev_i32_e32 v133, 31, v132
	v_lshlrev_b64 v[134:135], 13, v[130:131]
	v_lshl_add_u64 v[134:135], s[72:73], 0, v[134:135]
	v_lshlrev_b64 v[132:133], 2, v[132:133]
	v_lshl_add_u64 v[140:141], v[134:135], 0, v[132:133]
	v_or_b32_e32 v134, 16, v130
	v_ashrrev_i32_e32 v135, 31, v134
	v_lshlrev_b64 v[134:135], 13, v[134:135]
	v_lshl_add_u64 v[134:135], s[72:73], 0, v[134:135]
	v_lshl_add_u64 v[138:139], v[134:135], 0, v[132:133]
	v_or_b32_e32 v134, 32, v130
	v_ashrrev_i32_e32 v135, 31, v134
	v_lshlrev_b64 v[134:135], 13, v[134:135]
	v_lshl_add_u64 v[134:135], s[72:73], 0, v[134:135]
	v_lshl_add_u64 v[136:137], v[134:135], 0, v[132:133]
	v_or_b32_e32 v134, 48, v130
	v_ashrrev_i32_e32 v135, 31, v134
	v_lshlrev_b64 v[134:135], 13, v[134:135]
	v_lshl_add_u64 v[134:135], s[72:73], 0, v[134:135]
	v_lshl_add_u64 v[134:135], v[134:135], 0, v[132:133]
	global_load_dwordx4 v[180:183], v[140:141], off
	global_load_dwordx4 v[184:187], v[140:141], off offset:64
	global_load_dwordx4 v[188:191], v[138:139], off
	global_load_dwordx4 v[192:195], v[138:139], off offset:64
	global_load_dwordx4 v[196:199], v[136:137], off
	global_load_dwordx4 v[200:203], v[136:137], off offset:64
	global_load_dwordx4 v[204:207], v[134:135], off
	global_load_dwordx4 v[208:211], v[134:135], off offset:64
	s_waitcnt vmcnt(0)
; #define EPI_SCHED __builtin_amdgcn_sched_barrier(0)
; DI void gemm_resid(const u16* A, const u16* Bt, int K, const float* xin, float* xout, int bid, int nb, int tid) {
;     ...
;     for (int ai = 0; ai < 2; ++ai)
; #pragma unroll
;       for (int bj = 0; bj < 2; ++bj) {
;         float4 xi[4][2];
; #pragma unroll
;         for (int m = 0; m < 4; ++m)
; #pragma unroll
;           for (int n = 0; n < 2; ++n) xi[m][n] = *reinterpret_cast<const float4*>(xin + (size_t)ACC_ROW * 2048 + ACC_COL);
; #pragma unroll
;         for (int m = 0; m < 4; ++m)
; #pragma unroll
;           for (int n = 0; n < 2; ++n) {
;             const f32x4 v = acc[ai][bj][m][n];
;             float4 r; r.x = xi[m][n].x + v[0]; r.y = xi[m][n].y + v[1]; r.z = xi[m][n].z + v[2]; r.w = xi[m][n].w + v[3];
;             *reinterpret_cast<float4*>(xout + (size_t)ACC_ROW * 2048 + ACC_COL) = r;
;           }
;         EPI_SCHED;
;       }
	v_pk_add_f32 v[126:127], v[126:127], v[180:181]
	v_pk_add_f32 v[128:129], v[128:129], v[182:183]
	global_store_dwordx4 v[140:141], v[126:129], off
	v_pk_add_f32 v[122:123], v[122:123], v[184:185]
	v_pk_add_f32 v[124:125], v[124:125], v[186:187]
	global_store_dwordx4 v[140:141], v[122:125], off offset:64
	v_pk_add_f32 v[118:119], v[118:119], v[188:189]
	v_pk_add_f32 v[120:121], v[120:121], v[190:191]
	global_store_dwordx4 v[138:139], v[118:121], off
	v_pk_add_f32 v[114:115], v[114:115], v[192:193]
	v_pk_add_f32 v[116:117], v[116:117], v[194:195]
	global_store_dwordx4 v[138:139], v[114:117], off offset:64
	v_pk_add_f32 v[110:111], v[110:111], v[196:197]
	v_pk_add_f32 v[112:113], v[112:113], v[198:199]
	global_store_dwordx4 v[136:137], v[110:113], off
	v_pk_add_f32 v[106:107], v[106:107], v[200:201]
	v_pk_add_f32 v[108:109], v[108:109], v[202:203]
	global_store_dwordx4 v[136:137], v[106:109], off offset:64
	v_pk_add_f32 v[102:103], v[102:103], v[204:205]
	v_pk_add_f32 v[104:105], v[104:105], v[206:207]
	global_store_dwordx4 v[134:135], v[102:105], off
	v_pk_add_f32 v[98:99], v[98:99], v[208:209]
	v_pk_add_f32 v[100:101], v[100:101], v[210:211]
	global_store_dwordx4 v[134:135], v[98:101], off offset:64
	global_load_dwordx4 v[180:183], v[140:141], off offset:512
	global_load_dwordx4 v[184:187], v[140:141], off offset:576
	global_load_dwordx4 v[188:191], v[138:139], off offset:512
	global_load_dwordx4 v[192:195], v[138:139], off offset:576
	global_load_dwordx4 v[196:199], v[136:137], off offset:512
	global_load_dwordx4 v[200:203], v[136:137], off offset:576
	global_load_dwordx4 v[204:207], v[134:135], off offset:512
	global_load_dwordx4 v[208:211], v[134:135], off offset:576
	s_waitcnt vmcnt(0)
	v_pk_add_f32 v[94:95], v[94:95], v[180:181]
	v_pk_add_f32 v[96:97], v[96:97], v[182:183]
	global_store_dwordx4 v[140:141], v[94:97], off offset:512
	v_pk_add_f32 v[90:91], v[90:91], v[184:185]
	v_pk_add_f32 v[92:93], v[92:93], v[186:187]
	global_store_dwordx4 v[140:141], v[90:93], off offset:576
	v_pk_add_f32 v[86:87], v[86:87], v[188:189]
	v_pk_add_f32 v[88:89], v[88:89], v[190:191]
	global_store_dwordx4 v[138:139], v[86:89], off offset:512
	v_pk_add_f32 v[82:83], v[82:83], v[192:193]
	v_pk_add_f32 v[84:85], v[84:85], v[194:195]
	global_store_dwordx4 v[138:139], v[82:85], off offset:576
	v_pk_add_f32 v[78:79], v[78:79], v[196:197]
	v_pk_add_f32 v[80:81], v[80:81], v[198:199]
	global_store_dwordx4 v[136:137], v[78:81], off offset:512
	v_pk_add_f32 v[74:75], v[74:75], v[200:201]
	v_pk_add_f32 v[76:77], v[76:77], v[202:203]
	global_store_dwordx4 v[136:137], v[74:77], off offset:576
	v_pk_add_f32 v[70:71], v[70:71], v[204:205]
	v_pk_add_f32 v[72:73], v[72:73], v[206:207]
	global_store_dwordx4 v[134:135], v[70:73], off offset:512
	v_pk_add_f32 v[66:67], v[66:67], v[208:209]
	v_pk_add_f32 v[68:69], v[68:69], v[210:211]
	global_store_dwordx4 v[134:135], v[66:69], off offset:576
	s_nop 1
	v_add_u32_e32 v66, 0x80, v130
	v_ashrrev_i32_e32 v67, 31, v66
	v_lshlrev_b64 v[66:67], 13, v[66:67]
	v_lshl_add_u64 v[66:67], s[72:73], 0, v[66:67]
	v_lshl_add_u64 v[72:73], v[66:67], 0, v[132:133]
	v_add_u32_e32 v66, 0x90, v130
	v_ashrrev_i32_e32 v67, 31, v66
	v_lshlrev_b64 v[66:67], 13, v[66:67]
	v_lshl_add_u64 v[66:67], s[72:73], 0, v[66:67]
	v_lshl_add_u64 v[70:71], v[66:67], 0, v[132:133]
	v_add_u32_e32 v66, 0xa0, v130
	v_ashrrev_i32_e32 v67, 31, v66
	v_lshlrev_b64 v[66:67], 13, v[66:67]
	v_lshl_add_u64 v[66:67], s[72:73], 0, v[66:67]
	v_lshl_add_u64 v[68:69], v[66:67], 0, v[132:133]
	v_add_u32_e32 v66, 0xb0, v130
	v_ashrrev_i32_e32 v67, 31, v66
	v_lshlrev_b64 v[66:67], 13, v[66:67]
	v_lshl_add_u64 v[66:67], s[72:73], 0, v[66:67]
	v_lshl_add_u64 v[66:67], v[66:67], 0, v[132:133]
	global_load_dwordx4 v[180:183], v[72:73], off
	global_load_dwordx4 v[184:187], v[72:73], off offset:64
	global_load_dwordx4 v[188:191], v[70:71], off
	global_load_dwordx4 v[192:195], v[70:71], off offset:64
	global_load_dwordx4 v[196:199], v[68:69], off
	global_load_dwordx4 v[200:203], v[68:69], off offset:64
	global_load_dwordx4 v[204:207], v[66:67], off
	global_load_dwordx4 v[208:211], v[66:67], off offset:64
	s_waitcnt vmcnt(0)
	v_pk_add_f32 v[62:63], v[62:63], v[180:181]
	v_pk_add_f32 v[64:65], v[64:65], v[182:183]
	global_store_dwordx4 v[72:73], v[62:65], off
	v_pk_add_f32 v[58:59], v[58:59], v[184:185]
	v_pk_add_f32 v[60:61], v[60:61], v[186:187]
	global_store_dwordx4 v[72:73], v[58:61], off offset:64
	v_pk_add_f32 v[54:55], v[54:55], v[188:189]
	v_pk_add_f32 v[56:57], v[56:57], v[190:191]
	global_store_dwordx4 v[70:71], v[54:57], off
	v_pk_add_f32 v[50:51], v[50:51], v[192:193]
	v_pk_add_f32 v[52:53], v[52:53], v[194:195]
	global_store_dwordx4 v[70:71], v[50:53], off offset:64
	v_pk_add_f32 v[46:47], v[46:47], v[196:197]
	v_pk_add_f32 v[48:49], v[48:49], v[198:199]
	global_store_dwordx4 v[68:69], v[46:49], off
	v_pk_add_f32 v[42:43], v[42:43], v[200:201]
	v_pk_add_f32 v[44:45], v[44:45], v[202:203]
	global_store_dwordx4 v[68:69], v[42:45], off offset:64
	v_pk_add_f32 v[38:39], v[38:39], v[204:205]
	v_pk_add_f32 v[40:41], v[40:41], v[206:207]
	global_store_dwordx4 v[66:67], v[38:41], off
	v_pk_add_f32 v[34:35], v[34:35], v[208:209]
	v_pk_add_f32 v[36:37], v[36:37], v[210:211]
	global_store_dwordx4 v[66:67], v[34:37], off offset:64
	global_load_dwordx4 v[180:183], v[72:73], off offset:512
	global_load_dwordx4 v[184:187], v[72:73], off offset:576
	global_load_dwordx4 v[188:191], v[70:71], off offset:512
	global_load_dwordx4 v[192:195], v[70:71], off offset:576
	global_load_dwordx4 v[196:199], v[68:69], off offset:512
	global_load_dwordx4 v[200:203], v[68:69], off offset:576
	global_load_dwordx4 v[204:207], v[66:67], off offset:512
	global_load_dwordx4 v[208:211], v[66:67], off offset:576
	s_waitcnt vmcnt(0)
	v_pk_add_f32 v[30:31], v[30:31], v[180:181]
	v_pk_add_f32 v[32:33], v[32:33], v[182:183]
	global_store_dwordx4 v[72:73], v[30:33], off offset:512
	v_pk_add_f32 v[26:27], v[26:27], v[184:185]
	v_pk_add_f32 v[28:29], v[28:29], v[186:187]
	global_store_dwordx4 v[72:73], v[26:29], off offset:576
	v_pk_add_f32 v[22:23], v[22:23], v[188:189]
	v_pk_add_f32 v[24:25], v[24:25], v[190:191]
	global_store_dwordx4 v[70:71], v[22:25], off offset:512
	v_pk_add_f32 v[18:19], v[18:19], v[192:193]
	v_pk_add_f32 v[20:21], v[20:21], v[194:195]
	global_store_dwordx4 v[70:71], v[18:21], off offset:576
	v_pk_add_f32 v[14:15], v[14:15], v[196:197]
	v_pk_add_f32 v[16:17], v[16:17], v[198:199]
	global_store_dwordx4 v[68:69], v[14:17], off offset:512
	v_pk_add_f32 v[10:11], v[10:11], v[200:201]
	v_pk_add_f32 v[12:13], v[12:13], v[202:203]
	global_store_dwordx4 v[68:69], v[10:13], off offset:576
	v_pk_add_f32 v[6:7], v[6:7], v[204:205]
	v_pk_add_f32 v[8:9], v[8:9], v[206:207]
	global_store_dwordx4 v[66:67], v[6:9], off offset:512
	v_pk_add_f32 v[2:3], v[2:3], v[208:209]
	v_pk_add_f32 v[4:5], v[4:5], v[210:211]
	global_store_dwordx4 v[66:67], v[2:5], off offset:576
	s_and_b64 vcc, exec, s[0:1]
	s_mov_b32 s8, s5
	s_mov_b32 s7, s6
	s_cbranch_vccz .LBB0_29
; #define WAIT_V(n) asm volatile("s_waitcnt vmcnt(" #n ")" ::: "memory")
; #define BAR __builtin_amdgcn_s_barrier()
; template <class EPI>
; DI void gemm_stream(const u16* __restrict__ A, const u16* __restrict__ Bt, const int K, const int nM, const int nN,
;                     const int bid, const int nb, const int tid, EPI epi) {
;     ...
;   WAIT_V(0);
;   if (wr == 0) BAR;
	s_waitcnt vmcnt(0)
	s_movk_i32 s0, 0x100
	v_cmp_gt_u32_e32 vcc, s0, v239
	s_and_saveexec_b64 s[0:1], vcc
	s_cbranch_execz .LBB0_36
	s_barrier

.LBB0_46:
	v_or_b32_e32 v149, 0x10000, v146
	v_add_u32_e32 v154, 0x10400, v146
	ds_read_b128 v[150:153], v149
	ds_read_b128 v[154:157], v154
	v_add_u32_e32 v149, 0x10800, v146
	v_add_u32_e32 v162, 0x10c00, v146
	ds_read_b128 v[158:161], v149
	ds_read_b128 v[166:169], v162
	s_add_i32 s11, s10, -2
	s_cmp_lt_u32 s11, 30
	s_cselect_b32 s12, s9, s6
	s_cselect_b32 s13, s8, s5
	v_add_u32_e32 v162, 0xc000, v0
	v_add_u32_e32 v149, 0xfffc0000, v148
	v_readfirstlane_b32 s14, v162
	s_mov_b32 m0, s14
	ds_read_b128 v[170:173], v145
	ds_read_b128 v[174:177], v145 offset:1024
	ds_read_b128 v[180:183], v145 offset:2048
	ds_read_b128 v[184:187], v145 offset:3072
	ds_read_b128 v[188:191], v145 offset:4096
	ds_read_b128 v[192:195], v145 offset:5120
	ds_read_b128 v[196:199], v145 offset:6144
	ds_read_b128 v[200:203], v145 offset:7168
	global_load_lds_dwordx4 v149, s[80:81]
	v_add_u32_e32 v149, 0xe000, v0
	s_nop 0
	v_readfirstlane_b32 s14, v149
	s_mov_b32 m0, s14
	s_nop 0
	global_load_lds_dwordx4 v148, s[80:81]
	s_waitcnt lgkmcnt(8)
	v_or_b32_e32 v149, 0x14000, v146
	v_add_u32_e32 v162, 0x14400, v146
	ds_read_b128 v[204:207], v149
	ds_read_b128 v[208:211], v162
	v_add_u32_e32 v149, 0x14800, v146
	v_add_u32_e32 v162, 0x14c00, v146
	ds_read_b128 v[212:215], v149
	ds_read_b128 v[216:219], v162
	s_waitcnt vmcnt(8)
	s_waitcnt lgkmcnt(0)
	s_barrier
	v_mfma_f32_16x16x32_bf16 v[126:129], v[150:153], v[170:173], v[126:129]
	v_mfma_f32_16x16x32_bf16 v[118:121], v[158:161], v[170:173], v[118:121]
	v_mfma_f32_16x16x32_bf16 v[110:113], v[150:153], v[180:183], v[110:113]
	v_mfma_f32_16x16x32_bf16 v[102:105], v[158:161], v[180:183], v[102:105]
	v_mfma_f32_16x16x32_bf16 v[94:97], v[150:153], v[188:191], v[94:97]
	v_mfma_f32_16x16x32_bf16 v[86:89], v[158:161], v[188:191], v[86:89]
	v_mfma_f32_16x16x32_bf16 v[78:81], v[150:153], v[196:199], v[78:81]
	v_mfma_f32_16x16x32_bf16 v[70:73], v[158:161], v[196:199], v[70:73]
	v_mfma_f32_16x16x32_bf16 v[126:129], v[154:157], v[174:177], v[126:129]
	v_mfma_f32_16x16x32_bf16 v[118:121], v[166:169], v[174:177], v[118:121]
	v_mfma_f32_16x16x32_bf16 v[110:113], v[154:157], v[184:187], v[110:113]
	v_mfma_f32_16x16x32_bf16 v[102:105], v[166:169], v[184:187], v[102:105]
	v_mfma_f32_16x16x32_bf16 v[94:97], v[154:157], v[192:195], v[94:97]
	v_mfma_f32_16x16x32_bf16 v[86:89], v[166:169], v[192:195], v[86:89]
	v_mfma_f32_16x16x32_bf16 v[78:81], v[154:157], v[200:203], v[78:81]
	v_mfma_f32_16x16x32_bf16 v[70:73], v[166:169], v[200:203], v[70:73]
	v_mfma_f32_16x16x32_bf16 v[122:125], v[204:207], v[170:173], v[122:125]
	v_mfma_f32_16x16x32_bf16 v[114:117], v[212:215], v[170:173], v[114:117]
	v_mfma_f32_16x16x32_bf16 v[106:109], v[204:207], v[180:183], v[106:109]
	v_mfma_f32_16x16x32_bf16 v[98:101], v[212:215], v[180:183], v[98:101]
	v_mfma_f32_16x16x32_bf16 v[90:93], v[204:207], v[188:191], v[90:93]
	v_mfma_f32_16x16x32_bf16 v[82:85], v[212:215], v[188:191], v[82:85]
	v_mfma_f32_16x16x32_bf16 v[74:77], v[204:207], v[196:199], v[74:77]
	v_mfma_f32_16x16x32_bf16 v[66:69], v[212:215], v[196:199], v[66:69]
	v_mfma_f32_16x16x32_bf16 v[122:125], v[208:211], v[174:177], v[122:125]
	v_mfma_f32_16x16x32_bf16 v[114:117], v[216:219], v[174:177], v[114:117]
	v_mfma_f32_16x16x32_bf16 v[106:109], v[208:211], v[184:187], v[106:109]
	v_mfma_f32_16x16x32_bf16 v[98:101], v[216:219], v[184:187], v[98:101]
	v_mfma_f32_16x16x32_bf16 v[90:93], v[208:211], v[192:195], v[90:93]
	v_mfma_f32_16x16x32_bf16 v[82:85], v[216:219], v[192:195], v[82:85]
	v_mfma_f32_16x16x32_bf16 v[74:77], v[208:211], v[200:203], v[74:77]
	v_mfma_f32_16x16x32_bf16 v[66:69], v[216:219], v[200:203], v[66:69]
	s_barrier
	s_cselect_b32 s14, s10, 0
	s_lshl_b32 s12, s12, 11
	s_lshl_b32 s15, s14, 6
	s_or_b32 s16, s12, s15
	s_lshl_b32 s16, s16, 1
	v_readfirstlane_b32 s17, v132
	v_add_u32_e32 v149, s16, v130
	s_mov_b32 m0, s17
	s_nop 0
	global_load_lds_dwordx4 v149, s[82:83]
	v_add_u32_e32 v149, s16, v131
	v_readfirstlane_b32 s16, v133
	s_mov_b32 m0, s16
	s_nop 0
	global_load_lds_dwordx4 v149, s[82:83]
	s_lshl_b32 s16, s13, 11
	s_or_b32 s17, s16, s15
	s_lshl_b32 s17, s17, 1
	v_readfirstlane_b32 s18, v0
	v_add_u32_e32 v149, s17, v130
	s_mov_b32 m0, s18
	ds_read_b128 v[170:173], v145 offset:16384
	ds_read_b128 v[174:177], v145 offset:17408
	ds_read_b128 v[180:183], v145 offset:18432
	ds_read_b128 v[184:187], v145 offset:19456
	ds_read_b128 v[188:191], v145 offset:20480
	ds_read_b128 v[192:195], v145 offset:21504
	ds_read_b128 v[196:199], v145 offset:22528
	ds_read_b128 v[200:203], v145 offset:23552
	global_load_lds_dwordx4 v149, s[80:81]
	v_add_u32_e32 v149, s17, v131
	v_readfirstlane_b32 s17, v134
	s_mov_b32 m0, s17
	s_nop 0
	global_load_lds_dwordx4 v149, s[80:81]
	s_or_b32 s17, s12, 0x40000
	s_or_b32 s18, s17, s15
	s_lshl_b32 s18, s18, 1
	v_readfirstlane_b32 s19, v135
	v_add_u32_e32 v149, s18, v130
	s_mov_b32 m0, s19
	s_nop 0
	global_load_lds_dwordx4 v149, s[82:83]
	v_add_u32_e32 v149, s18, v131
	v_readfirstlane_b32 s18, v136
	s_mov_b32 m0, s18
	s_nop 0
	global_load_lds_dwordx4 v149, s[82:83]
	s_waitcnt vmcnt(8)
	s_waitcnt lgkmcnt(0)
	s_barrier
	v_mfma_f32_16x16x32_bf16 v[62:65], v[150:153], v[170:173], v[62:65]
	v_mfma_f32_16x16x32_bf16 v[54:57], v[158:161], v[170:173], v[54:57]
	v_mfma_f32_16x16x32_bf16 v[46:49], v[150:153], v[180:183], v[46:49]
	v_mfma_f32_16x16x32_bf16 v[38:41], v[158:161], v[180:183], v[38:41]
	v_mfma_f32_16x16x32_bf16 v[30:33], v[150:153], v[188:191], v[30:33]
	v_mfma_f32_16x16x32_bf16 v[22:25], v[158:161], v[188:191], v[22:25]
	v_mfma_f32_16x16x32_bf16 v[14:17], v[150:153], v[196:199], v[14:17]
	v_mfma_f32_16x16x32_bf16 v[6:9], v[158:161], v[196:199], v[6:9]
	v_mfma_f32_16x16x32_bf16 v[62:65], v[154:157], v[174:177], v[62:65]
	v_mfma_f32_16x16x32_bf16 v[54:57], v[166:169], v[174:177], v[54:57]
	v_mfma_f32_16x16x32_bf16 v[46:49], v[154:157], v[184:187], v[46:49]
	v_mfma_f32_16x16x32_bf16 v[38:41], v[166:169], v[184:187], v[38:41]
	v_mfma_f32_16x16x32_bf16 v[30:33], v[154:157], v[192:195], v[30:33]
	v_mfma_f32_16x16x32_bf16 v[22:25], v[166:169], v[192:195], v[22:25]
	v_mfma_f32_16x16x32_bf16 v[14:17], v[154:157], v[200:203], v[14:17]
	v_mfma_f32_16x16x32_bf16 v[6:9], v[166:169], v[200:203], v[6:9]
	v_mfma_f32_16x16x32_bf16 v[58:61], v[204:207], v[170:173], v[58:61]
	v_mfma_f32_16x16x32_bf16 v[50:53], v[212:215], v[170:173], v[50:53]
	v_mfma_f32_16x16x32_bf16 v[42:45], v[204:207], v[180:183], v[42:45]
	v_mfma_f32_16x16x32_bf16 v[34:37], v[212:215], v[180:183], v[34:37]
	v_mfma_f32_16x16x32_bf16 v[26:29], v[204:207], v[188:191], v[26:29]
	v_mfma_f32_16x16x32_bf16 v[18:21], v[212:215], v[188:191], v[18:21]
	v_mfma_f32_16x16x32_bf16 v[10:13], v[204:207], v[196:199], v[10:13]
	v_mfma_f32_16x16x32_bf16 v[2:5], v[212:215], v[196:199], v[2:5]
	v_mfma_f32_16x16x32_bf16 v[58:61], v[208:211], v[174:177], v[58:61]
	v_mfma_f32_16x16x32_bf16 v[50:53], v[216:219], v[174:177], v[50:53]
	v_mfma_f32_16x16x32_bf16 v[42:45], v[208:211], v[184:187], v[42:45]
	v_mfma_f32_16x16x32_bf16 v[34:37], v[216:219], v[184:187], v[34:37]
	v_mfma_f32_16x16x32_bf16 v[26:29], v[208:211], v[192:195], v[26:29]
	v_mfma_f32_16x16x32_bf16 v[18:21], v[216:219], v[192:195], v[18:21]
	v_mfma_f32_16x16x32_bf16 v[10:13], v[208:211], v[200:203], v[10:13]
	v_mfma_f32_16x16x32_bf16 v[2:5], v[216:219], v[200:203], v[2:5]
	s_barrier
	v_or_b32_e32 v149, 0x18000, v146
	v_add_u32_e32 v154, 0x18400, v146
	ds_read_b128 v[150:153], v149
	ds_read_b128 v[154:157], v154
	v_add_u32_e32 v149, 0x18800, v146
	v_add_u32_e32 v162, 0x18c00, v146
	ds_read_b128 v[158:161], v149
	ds_read_b128 v[166:169], v162
	s_lshl_b32 s13, s13, 12
	s_lshl_b32 s14, s14, 7
	s_add_i32 s13, s14, s13
	s_add_i32 s13, s13, 0x80000
	v_readfirstlane_b32 s14, v137
	v_add_u32_e32 v149, s13, v130
	s_mov_b32 m0, s14
	ds_read_b128 v[170:173], v145 offset:32768
	ds_read_b128 v[174:177], v145 offset:33792
	ds_read_b128 v[180:183], v145 offset:34816
	ds_read_b128 v[184:187], v145 offset:35840
	ds_read_b128 v[188:191], v145 offset:36864
	ds_read_b128 v[192:195], v145 offset:37888
	ds_read_b128 v[196:199], v145 offset:38912
	ds_read_b128 v[200:203], v145 offset:39936
	global_load_lds_dwordx4 v149, s[80:81]
	v_add_u32_e32 v149, s13, v131
	v_readfirstlane_b32 s13, v138
	s_mov_b32 m0, s13
	s_nop 0
	global_load_lds_dwordx4 v149, s[80:81]
	s_waitcnt lgkmcnt(8)
	v_or_b32_e32 v149, 0x1c000, v146
	v_add_u32_e32 v162, 0x1c400, v146
	ds_read_b128 v[204:207], v149
	ds_read_b128 v[208:211], v162
	v_add_u32_e32 v149, 0x1c800, v146
	v_add_u32_e32 v162, 0x1cc00, v146
	ds_read_b128 v[212:215], v149
	ds_read_b128 v[216:219], v162
	s_waitcnt vmcnt(8)
	s_waitcnt lgkmcnt(0)
	s_barrier
	v_mfma_f32_16x16x32_bf16 v[126:129], v[150:153], v[170:173], v[126:129]
	v_mfma_f32_16x16x32_bf16 v[118:121], v[158:161], v[170:173], v[118:121]
	v_mfma_f32_16x16x32_bf16 v[110:113], v[150:153], v[180:183], v[110:113]
	v_mfma_f32_16x16x32_bf16 v[102:105], v[158:161], v[180:183], v[102:105]
	v_mfma_f32_16x16x32_bf16 v[94:97], v[150:153], v[188:191], v[94:97]
	v_mfma_f32_16x16x32_bf16 v[86:89], v[158:161], v[188:191], v[86:89]
	v_mfma_f32_16x16x32_bf16 v[78:81], v[150:153], v[196:199], v[78:81]
	v_mfma_f32_16x16x32_bf16 v[70:73], v[158:161], v[196:199], v[70:73]
	v_mfma_f32_16x16x32_bf16 v[126:129], v[154:157], v[174:177], v[126:129]
	v_mfma_f32_16x16x32_bf16 v[118:121], v[166:169], v[174:177], v[118:121]
	v_mfma_f32_16x16x32_bf16 v[110:113], v[154:157], v[184:187], v[110:113]
	v_mfma_f32_16x16x32_bf16 v[102:105], v[166:169], v[184:187], v[102:105]
	v_mfma_f32_16x16x32_bf16 v[94:97], v[154:157], v[192:195], v[94:97]
	v_mfma_f32_16x16x32_bf16 v[86:89], v[166:169], v[192:195], v[86:89]
	v_mfma_f32_16x16x32_bf16 v[78:81], v[154:157], v[200:203], v[78:81]
	v_mfma_f32_16x16x32_bf16 v[70:73], v[166:169], v[200:203], v[70:73]
	v_mfma_f32_16x16x32_bf16 v[122:125], v[204:207], v[170:173], v[122:125]
	v_mfma_f32_16x16x32_bf16 v[114:117], v[212:215], v[170:173], v[114:117]
	v_mfma_f32_16x16x32_bf16 v[106:109], v[204:207], v[180:183], v[106:109]
	v_mfma_f32_16x16x32_bf16 v[98:101], v[212:215], v[180:183], v[98:101]
	v_mfma_f32_16x16x32_bf16 v[90:93], v[204:207], v[188:191], v[90:93]
	v_mfma_f32_16x16x32_bf16 v[82:85], v[212:215], v[188:191], v[82:85]
	v_mfma_f32_16x16x32_bf16 v[74:77], v[204:207], v[196:199], v[74:77]
	v_mfma_f32_16x16x32_bf16 v[66:69], v[212:215], v[196:199], v[66:69]
	v_mfma_f32_16x16x32_bf16 v[122:125], v[208:211], v[174:177], v[122:125]
	v_mfma_f32_16x16x32_bf16 v[114:117], v[216:219], v[174:177], v[114:117]
	v_mfma_f32_16x16x32_bf16 v[106:109], v[208:211], v[184:187], v[106:109]
	v_mfma_f32_16x16x32_bf16 v[98:101], v[216:219], v[184:187], v[98:101]
	v_mfma_f32_16x16x32_bf16 v[90:93], v[208:211], v[192:195], v[90:93]
	v_mfma_f32_16x16x32_bf16 v[82:85], v[216:219], v[192:195], v[82:85]
	v_mfma_f32_16x16x32_bf16 v[74:77], v[208:211], v[200:203], v[74:77]
	v_mfma_f32_16x16x32_bf16 v[66:69], v[216:219], v[200:203], v[66:69]
	s_barrier
; DI float sigmoidf_(float v) { return __builtin_amdgcn_rcpf(1.f + __expf(-v)); }
; #define EPI_SCHED __builtin_amdgcn_sched_barrier(0)
; DI void gemm_gateup(const Params& p, int bid, int nb, int tid) {
;     ...
;     _Pragma("unroll") for (int ai = 0; ai < 2; ++ai) _Pragma("unroll") for (int m = 0; m < 4; ++m) _Pragma("unroll") for (int n = 0; n < 2; ++n) {
;       const int col = pn * 128 + wc * 32 + n * 16 + fq * 4;
;       const int row = brow + ai * HALF + wr * 64 + m * 16 + fr;
;       const f32x4 g = acc[ai][0][m][n], uu = acc[ai][1][m][n];
;       uint2 w;
;       w.x = pk2(g[0] * sigmoidf_(g[0]) * uu[0], g[1] * sigmoidf_(g[1]) * uu[1]);
;       w.y = pk2(g[2] * sigmoidf_(g[2]) * uu[2], g[3] * sigmoidf_(g[3]) * uu[3]);
;       *reinterpret_cast<uint2*>(C + (size_t)row * DFF + col) = w;
;       EPI_SCHED;
	s_or_b32 s13, s15, 64
	s_or_b32 s12, s13, s12
	s_lshl_b32 s12, s12, 1
	v_readfirstlane_b32 s14, v139
	v_add_u32_e32 v149, s12, v130
	s_mov_b32 m0, s14
	s_nop 0
	global_load_lds_dwordx4 v149, s[82:83]
	v_add_u32_e32 v149, s12, v131
	v_readfirstlane_b32 s12, v140
	s_mov_b32 m0, s12
	s_nop 0
	global_load_lds_dwordx4 v149, s[82:83]
	s_or_b32 s12, s13, s16
	s_lshl_b32 s12, s12, 1
	v_readfirstlane_b32 s14, v141
	v_add_u32_e32 v149, s12, v130
	s_mov_b32 m0, s14
	ds_read_b128 v[170:173], v145 offset:49152
	ds_read_b128 v[174:177], v145 offset:50176
	ds_read_b128 v[180:183], v145 offset:51200
	ds_read_b128 v[184:187], v145 offset:52224
	ds_read_b128 v[188:191], v145 offset:53248
	ds_read_b128 v[192:195], v145 offset:54272
	ds_read_b128 v[196:199], v145 offset:55296
	ds_read_b128 v[200:203], v145 offset:56320
	global_load_lds_dwordx4 v149, s[80:81]
	v_add_u32_e32 v149, s12, v131
	v_readfirstlane_b32 s12, v142
	s_mov_b32 m0, s12
	s_nop 0
	global_load_lds_dwordx4 v149, s[80:81]
	s_or_b32 s12, s17, s13
	s_lshl_b32 s12, s12, 1
	v_readfirstlane_b32 s13, v143
	v_add_u32_e32 v149, s12, v130
	s_mov_b32 m0, s13
	s_nop 0
	global_load_lds_dwordx4 v149, s[82:83]
	v_add_u32_e32 v149, s12, v131
	v_readfirstlane_b32 s12, v144
	s_mov_b32 m0, s12
	s_nop 0
	global_load_lds_dwordx4 v149, s[82:83]
	s_waitcnt vmcnt(8)
	s_waitcnt lgkmcnt(0)
	s_barrier
	v_mfma_f32_16x16x32_bf16 v[62:65], v[150:153], v[170:173], v[62:65]
	v_mfma_f32_16x16x32_bf16 v[54:57], v[158:161], v[170:173], v[54:57]
	v_mfma_f32_16x16x32_bf16 v[46:49], v[150:153], v[180:183], v[46:49]
	v_mfma_f32_16x16x32_bf16 v[38:41], v[158:161], v[180:183], v[38:41]
	v_mfma_f32_16x16x32_bf16 v[30:33], v[150:153], v[188:191], v[30:33]
	v_mfma_f32_16x16x32_bf16 v[22:25], v[158:161], v[188:191], v[22:25]
	v_mfma_f32_16x16x32_bf16 v[14:17], v[150:153], v[196:199], v[14:17]
	v_mfma_f32_16x16x32_bf16 v[6:9], v[158:161], v[196:199], v[6:9]
	v_mfma_f32_16x16x32_bf16 v[62:65], v[154:157], v[174:177], v[62:65]
	v_mfma_f32_16x16x32_bf16 v[54:57], v[166:169], v[174:177], v[54:57]
	v_mfma_f32_16x16x32_bf16 v[46:49], v[154:157], v[184:187], v[46:49]
	v_mfma_f32_16x16x32_bf16 v[38:41], v[166:169], v[184:187], v[38:41]
	v_mfma_f32_16x16x32_bf16 v[30:33], v[154:157], v[192:195], v[30:33]
	v_mfma_f32_16x16x32_bf16 v[22:25], v[166:169], v[192:195], v[22:25]
	v_mfma_f32_16x16x32_bf16 v[14:17], v[154:157], v[200:203], v[14:17]
	v_mfma_f32_16x16x32_bf16 v[6:9], v[166:169], v[200:203], v[6:9]
	v_mfma_f32_16x16x32_bf16 v[58:61], v[204:207], v[170:173], v[58:61]
	v_mfma_f32_16x16x32_bf16 v[50:53], v[212:215], v[170:173], v[50:53]
	v_mfma_f32_16x16x32_bf16 v[42:45], v[204:207], v[180:183], v[42:45]
	v_mfma_f32_16x16x32_bf16 v[34:37], v[212:215], v[180:183], v[34:37]
	v_mfma_f32_16x16x32_bf16 v[26:29], v[204:207], v[188:191], v[26:29]
	v_mfma_f32_16x16x32_bf16 v[18:21], v[212:215], v[188:191], v[18:21]
	v_mfma_f32_16x16x32_bf16 v[10:13], v[204:207], v[196:199], v[10:13]
	v_mfma_f32_16x16x32_bf16 v[2:5], v[212:215], v[196:199], v[2:5]
	v_mfma_f32_16x16x32_bf16 v[58:61], v[208:211], v[174:177], v[58:61]
	v_mfma_f32_16x16x32_bf16 v[50:53], v[216:219], v[174:177], v[50:53]
	v_mfma_f32_16x16x32_bf16 v[42:45], v[208:211], v[184:187], v[42:45]
	v_mfma_f32_16x16x32_bf16 v[34:37], v[216:219], v[184:187], v[34:37]
	v_mfma_f32_16x16x32_bf16 v[26:29], v[208:211], v[192:195], v[26:29]
	v_mfma_f32_16x16x32_bf16 v[18:21], v[216:219], v[192:195], v[18:21]
	v_mfma_f32_16x16x32_bf16 v[10:13], v[208:211], v[200:203], v[10:13]
	v_mfma_f32_16x16x32_bf16 v[2:5], v[216:219], v[200:203], v[2:5]
	s_add_i32 s10, s10, 2
	s_cmp_gt_u32 s11, 29
	v_add_u32_e32 v148, 0x100, v148
	s_barrier
	s_cbranch_scc0 .LBB0_46
	v_mov_b32_e32 v148, v239
	s_lshl_b32 s7, s7, 7
	v_lshrrev_b32_e32 v149, 1, v148
	v_lshrrev_b32_e32 v150, 2, v148
	v_and_b32_e32 v149, 0x60, v149
	v_and_b32_e32 v150, 12, v150
	v_or3_b32 v150, v149, s7, v150
	v_ashrrev_i32_e32 v149, 2, v148
	v_and_b32_e32 v149, 0xffffffc0, v149
	v_and_or_b32 v148, v148, 15, s8
	v_add_u32_e32 v148, v148, v149
	v_mul_f32_e32 v149, 0xbfb8aa3b, v126
	v_exp_f32_e32 v149, v149
	s_movk_i32 s7, 0x2c00
	v_ashrrev_i32_e32 v151, 31, v150
	v_add_f32_e32 v149, 1.0, v149
	v_rcp_f32_e32 v152, v149
	v_mul_f32_e32 v149, 0xbfb8aa3b, v127
	v_exp_f32_e32 v149, v149
	s_nop 0
	v_add_f32_e32 v149, 1.0, v149
	v_rcp_f32_e32 v153, v149
	s_nop 0
	v_pk_mul_f32 v[126:127], v[126:127], v[152:153]
	s_nop 0
	v_pk_mul_f32 v[122:123], v[126:127], v[122:123]
	s_nop 0
	v_cvt_pk_bf16_f32 v126, v122, v123
	v_mul_f32_e32 v122, 0xbfb8aa3b, v128
	v_mul_f32_e32 v123, 0xbfb8aa3b, v129
	v_exp_f32_e32 v122, v122
	v_exp_f32_e32 v123, v123
	v_add_f32_e32 v122, 1.0, v122
	v_add_f32_e32 v123, 1.0, v123
	v_rcp_f32_e32 v122, v122
	v_rcp_f32_e32 v123, v123
	s_nop 0
	v_pk_mul_f32 v[122:123], v[128:129], v[122:123]
	s_nop 0
	v_pk_mul_f32 v[122:123], v[122:123], v[124:125]
	v_lshlrev_b64 v[124:125], 1, v[150:151]
	v_cvt_pk_bf16_f32 v127, v122, v123
	v_mov_b64_e32 v[122:123], s[76:77]
	v_mad_i64_i32 v[128:129], s[8:9], v148, s7, v[122:123]
	v_lshl_add_u64 v[128:129], v[128:129], 0, v[124:125]
	global_store_dwordx2 v[128:129], v[126:127], off
	v_mul_f32_e32 v126, 0xbfb8aa3b, v118
	v_mul_f32_e32 v127, 0xbfb8aa3b, v119
	v_exp_f32_e32 v126, v126
	v_exp_f32_e32 v127, v127
	v_add_f32_e32 v126, 1.0, v126
	v_add_f32_e32 v127, 1.0, v127
	v_rcp_f32_e32 v126, v126
	v_rcp_f32_e32 v127, v127
	s_nop 0
	v_pk_mul_f32 v[118:119], v[118:119], v[126:127]
	s_nop 0
	v_pk_mul_f32 v[114:115], v[118:119], v[114:115]
	s_nop 0
	v_cvt_pk_bf16_f32 v114, v114, v115
	v_mul_f32_e32 v115, 0xbfb8aa3b, v120
	v_exp_f32_e32 v115, v115
	s_nop 0
	v_add_f32_e32 v115, 1.0, v115
	v_rcp_f32_e32 v118, v115
; DI float sigmoidf_(float v) { return __builtin_amdgcn_rcpf(1.f + __expf(-v)); }
; #define EPI_SCHED __builtin_amdgcn_sched_barrier(0)
; DI void gemm_gateup(const Params& p, int bid, int nb, int tid) {
;     ...
;     _Pragma("unroll") for (int ai = 0; ai < 2; ++ai) _Pragma("unroll") for (int m = 0; m < 4; ++m) _Pragma("unroll") for (int n = 0; n < 2; ++n) {
;       const int col = pn * 128 + wc * 32 + n * 16 + fq * 4;
;       const int row = brow + ai * HALF + wr * 64 + m * 16 + fr;
;       const f32x4 g = acc[ai][0][m][n], uu = acc[ai][1][m][n];
;       uint2 w;
;       w.x = pk2(g[0] * sigmoidf_(g[0]) * uu[0], g[1] * sigmoidf_(g[1]) * uu[1]);
;       w.y = pk2(g[2] * sigmoidf_(g[2]) * uu[2], g[3] * sigmoidf_(g[3]) * uu[3]);
;       *reinterpret_cast<uint2*>(C + (size_t)row * DFF + col) = w;
;       EPI_SCHED;
	v_mul_f32_e32 v115, 0xbfb8aa3b, v121
	v_exp_f32_e32 v115, v115
	s_nop 0
	v_add_f32_e32 v115, 1.0, v115
	v_rcp_f32_e32 v119, v115
	s_nop 0
	v_pk_mul_f32 v[118:119], v[120:121], v[118:119]
	s_nop 0
	v_pk_mul_f32 v[116:117], v[118:119], v[116:117]
	s_nop 0
	v_cvt_pk_bf16_f32 v115, v116, v117
	global_store_dwordx2 v[128:129], v[114:115], off offset:32
	v_mul_f32_e32 v114, 0xbfb8aa3b, v110
	v_mul_f32_e32 v115, 0xbfb8aa3b, v111
	v_exp_f32_e32 v114, v114
	v_exp_f32_e32 v115, v115
	v_or_b32_e32 v116, 16, v148
	v_add_f32_e32 v114, 1.0, v114
	v_add_f32_e32 v115, 1.0, v115
	v_rcp_f32_e32 v114, v114
	v_rcp_f32_e32 v115, v115
	s_nop 0
	v_pk_mul_f32 v[110:111], v[110:111], v[114:115]
	s_nop 0
	v_pk_mul_f32 v[106:107], v[110:111], v[106:107]
	s_nop 0
	v_cvt_pk_bf16_f32 v106, v106, v107
	v_mul_f32_e32 v107, 0xbfb8aa3b, v112
	v_exp_f32_e32 v107, v107
	s_nop 0
	v_add_f32_e32 v107, 1.0, v107
	v_rcp_f32_e32 v110, v107
	v_mul_f32_e32 v107, 0xbfb8aa3b, v113
	v_exp_f32_e32 v107, v107
	s_nop 0
	v_add_f32_e32 v107, 1.0, v107
	v_rcp_f32_e32 v111, v107
	s_nop 0
	v_pk_mul_f32 v[110:111], v[112:113], v[110:111]
	s_nop 0
	v_pk_mul_f32 v[108:109], v[110:111], v[108:109]
	s_nop 0
	v_cvt_pk_bf16_f32 v107, v108, v109
	v_mad_i64_i32 v[108:109], s[8:9], v116, s7, v[122:123]
	v_lshl_add_u64 v[108:109], v[108:109], 0, v[124:125]
	global_store_dwordx2 v[108:109], v[106:107], off
	v_mul_f32_e32 v106, 0xbfb8aa3b, v102
	v_mul_f32_e32 v107, 0xbfb8aa3b, v103
	v_exp_f32_e32 v106, v106
	v_exp_f32_e32 v107, v107
	v_add_f32_e32 v106, 1.0, v106
	v_add_f32_e32 v107, 1.0, v107
	v_rcp_f32_e32 v106, v106
	v_rcp_f32_e32 v107, v107
	s_nop 0
	v_pk_mul_f32 v[102:103], v[102:103], v[106:107]
	s_nop 0
	v_pk_mul_f32 v[98:99], v[102:103], v[98:99]
	s_nop 0
	v_cvt_pk_bf16_f32 v98, v98, v99
	v_mul_f32_e32 v99, 0xbfb8aa3b, v104
	v_exp_f32_e32 v99, v99
	s_nop 0
	v_add_f32_e32 v99, 1.0, v99
	v_rcp_f32_e32 v102, v99
	v_mul_f32_e32 v99, 0xbfb8aa3b, v105
	v_exp_f32_e32 v99, v99
	s_nop 0
	v_add_f32_e32 v99, 1.0, v99
	v_rcp_f32_e32 v103, v99
	s_nop 0
	v_pk_mul_f32 v[102:103], v[104:105], v[102:103]
	s_nop 0
	v_pk_mul_f32 v[100:101], v[102:103], v[100:101]
	s_nop 0
	v_cvt_pk_bf16_f32 v99, v100, v101
	global_store_dwordx2 v[108:109], v[98:99], off offset:32
	v_mul_f32_e32 v98, 0xbfb8aa3b, v94
	v_mul_f32_e32 v99, 0xbfb8aa3b, v95
	v_exp_f32_e32 v98, v98
	v_exp_f32_e32 v99, v99
	v_or_b32_e32 v100, 32, v148
	v_add_f32_e32 v98, 1.0, v98
	v_add_f32_e32 v99, 1.0, v99
	v_rcp_f32_e32 v98, v98
	v_rcp_f32_e32 v99, v99
	s_nop 0
	v_pk_mul_f32 v[94:95], v[94:95], v[98:99]
	s_nop 0
	v_pk_mul_f32 v[90:91], v[94:95], v[90:91]
	s_nop 0
	v_cvt_pk_bf16_f32 v90, v90, v91
	v_mul_f32_e32 v91, 0xbfb8aa3b, v96
	v_exp_f32_e32 v91, v91
	s_nop 0
	v_add_f32_e32 v91, 1.0, v91
	v_rcp_f32_e32 v94, v91
	v_mul_f32_e32 v91, 0xbfb8aa3b, v97
	v_exp_f32_e32 v91, v91
	s_nop 0
	v_add_f32_e32 v91, 1.0, v91
	v_rcp_f32_e32 v95, v91
	s_nop 0
	v_pk_mul_f32 v[94:95], v[96:97], v[94:95]
	s_nop 0
	v_pk_mul_f32 v[92:93], v[94:95], v[92:93]
	s_nop 0
	v_cvt_pk_bf16_f32 v91, v92, v93
	v_mad_i64_i32 v[92:93], s[8:9], v100, s7, v[122:123]
	v_lshl_add_u64 v[92:93], v[92:93], 0, v[124:125]
	global_store_dwordx2 v[92:93], v[90:91], off
	v_mul_f32_e32 v90, 0xbfb8aa3b, v86
	v_mul_f32_e32 v91, 0xbfb8aa3b, v87
	v_exp_f32_e32 v90, v90
	v_exp_f32_e32 v91, v91
	v_add_f32_e32 v90, 1.0, v90
	v_add_f32_e32 v91, 1.0, v91
	v_rcp_f32_e32 v90, v90
	v_rcp_f32_e32 v91, v91
	s_nop 0
	v_pk_mul_f32 v[86:87], v[86:87], v[90:91]
	s_nop 0
	v_pk_mul_f32 v[82:83], v[86:87], v[82:83]
	s_nop 0
	v_cvt_pk_bf16_f32 v82, v82, v83
	v_mul_f32_e32 v83, 0xbfb8aa3b, v88
	v_exp_f32_e32 v83, v83
	s_nop 0
	v_add_f32_e32 v83, 1.0, v83
	v_rcp_f32_e32 v86, v83
	v_mul_f32_e32 v83, 0xbfb8aa3b, v89
	v_exp_f32_e32 v83, v83
	s_nop 0
	v_add_f32_e32 v83, 1.0, v83
	v_rcp_f32_e32 v87, v83
	s_nop 0
	v_pk_mul_f32 v[86:87], v[88:89], v[86:87]
	s_nop 0
	v_pk_mul_f32 v[84:85], v[86:87], v[84:85]
	s_nop 0
	v_cvt_pk_bf16_f32 v83, v84, v85
	global_store_dwordx2 v[92:93], v[82:83], off offset:32
	v_mul_f32_e32 v82, 0xbfb8aa3b, v78
	v_mul_f32_e32 v83, 0xbfb8aa3b, v79
	v_exp_f32_e32 v82, v82
	v_exp_f32_e32 v83, v83
	v_or_b32_e32 v84, 48, v148
	v_add_f32_e32 v82, 1.0, v82
	v_add_f32_e32 v83, 1.0, v83
	v_rcp_f32_e32 v82, v82
	v_rcp_f32_e32 v83, v83
	s_nop 0
	v_pk_mul_f32 v[78:79], v[78:79], v[82:83]
	s_nop 0
	v_pk_mul_f32 v[74:75], v[78:79], v[74:75]
	s_nop 0
	v_cvt_pk_bf16_f32 v74, v74, v75
	v_mul_f32_e32 v75, 0xbfb8aa3b, v80
	v_exp_f32_e32 v75, v75
	s_nop 0
	v_add_f32_e32 v75, 1.0, v75
	v_rcp_f32_e32 v78, v75
	v_mul_f32_e32 v75, 0xbfb8aa3b, v81
	v_exp_f32_e32 v75, v75
	s_nop 0
	v_add_f32_e32 v75, 1.0, v75
	v_rcp_f32_e32 v79, v75
	s_nop 0
	v_pk_mul_f32 v[78:79], v[80:81], v[78:79]
	s_nop 0
	v_pk_mul_f32 v[76:77], v[78:79], v[76:77]
	s_nop 0
	v_cvt_pk_bf16_f32 v75, v76, v77
	v_mad_i64_i32 v[76:77], s[8:9], v84, s7, v[122:123]
	v_lshl_add_u64 v[76:77], v[76:77], 0, v[124:125]
	global_store_dwordx2 v[76:77], v[74:75], off
	v_mul_f32_e32 v74, 0xbfb8aa3b, v70
	v_mul_f32_e32 v75, 0xbfb8aa3b, v71
	v_exp_f32_e32 v74, v74
	v_exp_f32_e32 v75, v75
	v_add_f32_e32 v74, 1.0, v74
	v_add_f32_e32 v75, 1.0, v75
	v_rcp_f32_e32 v74, v74
	v_rcp_f32_e32 v75, v75
	s_nop 0
	v_pk_mul_f32 v[70:71], v[70:71], v[74:75]
	s_nop 0
	v_pk_mul_f32 v[66:67], v[70:71], v[66:67]
	s_nop 0
	v_cvt_pk_bf16_f32 v66, v66, v67
	v_mul_f32_e32 v67, 0xbfb8aa3b, v72
	v_exp_f32_e32 v67, v67
	s_nop 0
	v_add_f32_e32 v67, 1.0, v67
	v_rcp_f32_e32 v70, v67
	v_mul_f32_e32 v67, 0xbfb8aa3b, v73
	v_exp_f32_e32 v67, v67
	s_nop 0
	v_add_f32_e32 v67, 1.0, v67
	v_rcp_f32_e32 v71, v67
	s_nop 0
	v_pk_mul_f32 v[70:71], v[72:73], v[70:71]
	s_nop 0
	v_pk_mul_f32 v[68:69], v[70:71], v[68:69]
; DI float sigmoidf_(float v) { return __builtin_amdgcn_rcpf(1.f + __expf(-v)); }
; #define EPI_SCHED __builtin_amdgcn_sched_barrier(0)
; DI void gemm_gateup(const Params& p, int bid, int nb, int tid) {
;     ...
;     _Pragma("unroll") for (int ai = 0; ai < 2; ++ai) _Pragma("unroll") for (int m = 0; m < 4; ++m) _Pragma("unroll") for (int n = 0; n < 2; ++n) {
;       const int col = pn * 128 + wc * 32 + n * 16 + fq * 4;
;       const int row = brow + ai * HALF + wr * 64 + m * 16 + fr;
;       const f32x4 g = acc[ai][0][m][n], uu = acc[ai][1][m][n];
;       uint2 w;
;       w.x = pk2(g[0] * sigmoidf_(g[0]) * uu[0], g[1] * sigmoidf_(g[1]) * uu[1]);
;       w.y = pk2(g[2] * sigmoidf_(g[2]) * uu[2], g[3] * sigmoidf_(g[3]) * uu[3]);
;       *reinterpret_cast<uint2*>(C + (size_t)row * DFF + col) = w;
;       EPI_SCHED;
	s_nop 0
	v_cvt_pk_bf16_f32 v67, v68, v69
	global_store_dwordx2 v[76:77], v[66:67], off offset:32
	v_mul_f32_e32 v66, 0xbfb8aa3b, v62
	v_mul_f32_e32 v67, 0xbfb8aa3b, v63
	v_exp_f32_e32 v66, v66
	v_exp_f32_e32 v67, v67
	v_add_u32_e32 v68, 0x80, v148
	v_add_f32_e32 v66, 1.0, v66
	v_add_f32_e32 v67, 1.0, v67
	v_rcp_f32_e32 v66, v66
	v_rcp_f32_e32 v67, v67
	s_nop 0
	v_pk_mul_f32 v[62:63], v[62:63], v[66:67]
	s_nop 0
	v_pk_mul_f32 v[58:59], v[62:63], v[58:59]
	s_nop 0
	v_cvt_pk_bf16_f32 v58, v58, v59
	v_mul_f32_e32 v59, 0xbfb8aa3b, v64
	v_exp_f32_e32 v59, v59
	s_nop 0
	v_add_f32_e32 v59, 1.0, v59
	v_rcp_f32_e32 v62, v59
	v_mul_f32_e32 v59, 0xbfb8aa3b, v65
	v_exp_f32_e32 v59, v59
	s_nop 0
	v_add_f32_e32 v59, 1.0, v59
	v_rcp_f32_e32 v63, v59
	s_nop 0
	v_pk_mul_f32 v[62:63], v[64:65], v[62:63]
	s_nop 0
	v_pk_mul_f32 v[60:61], v[62:63], v[60:61]
	s_nop 0
	v_cvt_pk_bf16_f32 v59, v60, v61
	v_mad_i64_i32 v[60:61], s[8:9], v68, s7, v[122:123]
	v_lshl_add_u64 v[60:61], v[60:61], 0, v[124:125]
	global_store_dwordx2 v[60:61], v[58:59], off
	v_mul_f32_e32 v58, 0xbfb8aa3b, v54
	v_mul_f32_e32 v59, 0xbfb8aa3b, v55
	v_exp_f32_e32 v58, v58
	v_exp_f32_e32 v59, v59
	v_add_f32_e32 v58, 1.0, v58
	v_add_f32_e32 v59, 1.0, v59
	v_rcp_f32_e32 v58, v58
	v_rcp_f32_e32 v59, v59
	s_nop 0
	v_pk_mul_f32 v[54:55], v[54:55], v[58:59]
	s_nop 0
	v_pk_mul_f32 v[50:51], v[54:55], v[50:51]
	s_nop 0
	v_cvt_pk_bf16_f32 v50, v50, v51
	v_mul_f32_e32 v51, 0xbfb8aa3b, v56
	v_exp_f32_e32 v51, v51
	s_nop 0
	v_add_f32_e32 v51, 1.0, v51
	v_rcp_f32_e32 v54, v51
	v_mul_f32_e32 v51, 0xbfb8aa3b, v57
	v_exp_f32_e32 v51, v51
	s_nop 0
	v_add_f32_e32 v51, 1.0, v51
	v_rcp_f32_e32 v55, v51
	s_nop 0
	v_pk_mul_f32 v[54:55], v[56:57], v[54:55]
	s_nop 0
	v_pk_mul_f32 v[52:53], v[54:55], v[52:53]
	s_nop 0
	v_cvt_pk_bf16_f32 v51, v52, v53
	global_store_dwordx2 v[60:61], v[50:51], off offset:32
	v_mul_f32_e32 v50, 0xbfb8aa3b, v46
	v_mul_f32_e32 v51, 0xbfb8aa3b, v47
	v_exp_f32_e32 v50, v50
	v_exp_f32_e32 v51, v51
	v_add_u32_e32 v52, 0x90, v148
	v_add_f32_e32 v50, 1.0, v50
	v_add_f32_e32 v51, 1.0, v51
	v_rcp_f32_e32 v50, v50
	v_rcp_f32_e32 v51, v51
	s_nop 0
	v_pk_mul_f32 v[46:47], v[46:47], v[50:51]
	s_nop 0
	v_pk_mul_f32 v[42:43], v[46:47], v[42:43]
	s_nop 0
	v_cvt_pk_bf16_f32 v42, v42, v43
	v_mul_f32_e32 v43, 0xbfb8aa3b, v48
	v_exp_f32_e32 v43, v43
	s_nop 0
	v_add_f32_e32 v43, 1.0, v43
	v_rcp_f32_e32 v46, v43
	v_mul_f32_e32 v43, 0xbfb8aa3b, v49
	v_exp_f32_e32 v43, v43
	s_nop 0
	v_add_f32_e32 v43, 1.0, v43
	v_rcp_f32_e32 v47, v43
	s_nop 0
	v_pk_mul_f32 v[46:47], v[48:49], v[46:47]
	s_nop 0
	v_pk_mul_f32 v[44:45], v[46:47], v[44:45]
	s_nop 0
	v_cvt_pk_bf16_f32 v43, v44, v45
	v_mad_i64_i32 v[44:45], s[8:9], v52, s7, v[122:123]
	v_lshl_add_u64 v[44:45], v[44:45], 0, v[124:125]
	global_store_dwordx2 v[44:45], v[42:43], off
	v_mul_f32_e32 v42, 0xbfb8aa3b, v38
	v_mul_f32_e32 v43, 0xbfb8aa3b, v39
	v_exp_f32_e32 v42, v42
	v_exp_f32_e32 v43, v43
	v_add_f32_e32 v42, 1.0, v42
	v_add_f32_e32 v43, 1.0, v43
	v_rcp_f32_e32 v42, v42
	v_rcp_f32_e32 v43, v43
	s_nop 0
	v_pk_mul_f32 v[38:39], v[38:39], v[42:43]
	s_nop 0
	v_pk_mul_f32 v[34:35], v[38:39], v[34:35]
	s_nop 0
	v_cvt_pk_bf16_f32 v34, v34, v35
	v_mul_f32_e32 v35, 0xbfb8aa3b, v40
	v_exp_f32_e32 v35, v35
	s_nop 0
	v_add_f32_e32 v35, 1.0, v35
	v_rcp_f32_e32 v38, v35
	v_mul_f32_e32 v35, 0xbfb8aa3b, v41
	v_exp_f32_e32 v35, v35
	s_nop 0
	v_add_f32_e32 v35, 1.0, v35
	v_rcp_f32_e32 v39, v35
	s_nop 0
	v_pk_mul_f32 v[38:39], v[40:41], v[38:39]
	s_nop 0
	v_pk_mul_f32 v[36:37], v[38:39], v[36:37]
	s_nop 0
	v_cvt_pk_bf16_f32 v35, v36, v37
	global_store_dwordx2 v[44:45], v[34:35], off offset:32
	v_mul_f32_e32 v34, 0xbfb8aa3b, v30
; DI float sigmoidf_(float v) { return __builtin_amdgcn_rcpf(1.f + __expf(-v)); }
; #define WAIT_V(n) asm volatile("s_waitcnt vmcnt(" #n ")" ::: "memory")
; #define BAR __builtin_amdgcn_s_barrier()
; #define EPI_SCHED __builtin_amdgcn_sched_barrier(0)
; template <class EPI>
; DI void gemm_stream(const u16* __restrict__ A, const u16* __restrict__ Bt, const int K, const int nM, const int nN,
;                     const int bid, const int nb, const int tid, EPI epi) {
;     ...
;   WAIT_V(0);
;   if (wr == 0) BAR;
; DI void gemm_gateup(const Params& p, int bid, int nb, int tid) {
;     ...
;     _Pragma("unroll") for (int ai = 0; ai < 2; ++ai) _Pragma("unroll") for (int m = 0; m < 4; ++m) _Pragma("unroll") for (int n = 0; n < 2; ++n) {
;       const int col = pn * 128 + wc * 32 + n * 16 + fq * 4;
;       const int row = brow + ai * HALF + wr * 64 + m * 16 + fr;
;       const f32x4 g = acc[ai][0][m][n], uu = acc[ai][1][m][n];
;       uint2 w;
;       w.x = pk2(g[0] * sigmoidf_(g[0]) * uu[0], g[1] * sigmoidf_(g[1]) * uu[1]);
;       w.y = pk2(g[2] * sigmoidf_(g[2]) * uu[2], g[3] * sigmoidf_(g[3]) * uu[3]);
;       *reinterpret_cast<uint2*>(C + (size_t)row * DFF + col) = w;
;       EPI_SCHED;
	v_mul_f32_e32 v35, 0xbfb8aa3b, v31
	v_exp_f32_e32 v34, v34
	v_exp_f32_e32 v35, v35
	v_add_u32_e32 v36, 0xa0, v148
	v_add_f32_e32 v34, 1.0, v34
	v_add_f32_e32 v35, 1.0, v35
	v_rcp_f32_e32 v34, v34
	v_rcp_f32_e32 v35, v35
	s_nop 0
	v_pk_mul_f32 v[30:31], v[30:31], v[34:35]
	s_nop 0
	v_pk_mul_f32 v[26:27], v[30:31], v[26:27]
	s_nop 0
	v_cvt_pk_bf16_f32 v26, v26, v27
	v_mul_f32_e32 v27, 0xbfb8aa3b, v32
	v_exp_f32_e32 v27, v27
	s_nop 0
	v_add_f32_e32 v27, 1.0, v27
	v_rcp_f32_e32 v30, v27
	v_mul_f32_e32 v27, 0xbfb8aa3b, v33
	v_exp_f32_e32 v27, v27
	s_nop 0
	v_add_f32_e32 v27, 1.0, v27
	v_rcp_f32_e32 v31, v27
	s_nop 0
	v_pk_mul_f32 v[30:31], v[32:33], v[30:31]
	s_nop 0
	v_pk_mul_f32 v[28:29], v[30:31], v[28:29]
	s_nop 0
	v_cvt_pk_bf16_f32 v27, v28, v29
	v_mad_i64_i32 v[28:29], s[8:9], v36, s7, v[122:123]
	v_lshl_add_u64 v[28:29], v[28:29], 0, v[124:125]
	global_store_dwordx2 v[28:29], v[26:27], off
	v_mul_f32_e32 v26, 0xbfb8aa3b, v22
	v_mul_f32_e32 v27, 0xbfb8aa3b, v23
	v_exp_f32_e32 v26, v26
	v_exp_f32_e32 v27, v27
	v_add_f32_e32 v26, 1.0, v26
	v_add_f32_e32 v27, 1.0, v27
	v_rcp_f32_e32 v26, v26
	v_rcp_f32_e32 v27, v27
	s_nop 0
	v_pk_mul_f32 v[22:23], v[22:23], v[26:27]
	s_nop 0
	v_pk_mul_f32 v[18:19], v[22:23], v[18:19]
	s_nop 0
	v_cvt_pk_bf16_f32 v18, v18, v19
	v_mul_f32_e32 v19, 0xbfb8aa3b, v24
	v_exp_f32_e32 v19, v19
	s_nop 0
	v_add_f32_e32 v19, 1.0, v19
	v_rcp_f32_e32 v22, v19
	v_mul_f32_e32 v19, 0xbfb8aa3b, v25
	v_exp_f32_e32 v19, v19
	s_nop 0
	v_add_f32_e32 v19, 1.0, v19
	v_rcp_f32_e32 v23, v19
	s_nop 0
	v_pk_mul_f32 v[22:23], v[24:25], v[22:23]
	s_nop 0
	v_pk_mul_f32 v[20:21], v[22:23], v[20:21]
	s_nop 0
	v_cvt_pk_bf16_f32 v19, v20, v21
	global_store_dwordx2 v[28:29], v[18:19], off offset:32
	v_mul_f32_e32 v18, 0xbfb8aa3b, v14
	v_mul_f32_e32 v19, 0xbfb8aa3b, v15
	v_exp_f32_e32 v18, v18
	v_exp_f32_e32 v19, v19
	v_add_u32_e32 v20, 0xb0, v148
	v_add_f32_e32 v18, 1.0, v18
	v_add_f32_e32 v19, 1.0, v19
	v_rcp_f32_e32 v18, v18
	v_rcp_f32_e32 v19, v19
	s_nop 0
	v_pk_mul_f32 v[14:15], v[14:15], v[18:19]
	s_nop 0
	v_pk_mul_f32 v[10:11], v[14:15], v[10:11]
	s_nop 0
	v_cvt_pk_bf16_f32 v10, v10, v11
	v_mul_f32_e32 v11, 0xbfb8aa3b, v16
	v_exp_f32_e32 v11, v11
	s_nop 0
	v_add_f32_e32 v11, 1.0, v11
	v_rcp_f32_e32 v14, v11
	v_mul_f32_e32 v11, 0xbfb8aa3b, v17
	v_exp_f32_e32 v11, v11
	s_nop 0
	v_add_f32_e32 v11, 1.0, v11
	v_rcp_f32_e32 v15, v11
	s_nop 0
	v_pk_mul_f32 v[14:15], v[16:17], v[14:15]
	s_nop 0
	v_pk_mul_f32 v[12:13], v[14:15], v[12:13]
	s_nop 0
	v_cvt_pk_bf16_f32 v11, v12, v13
	v_mad_i64_i32 v[12:13], s[8:9], v20, s7, v[122:123]
	v_lshl_add_u64 v[12:13], v[12:13], 0, v[124:125]
	global_store_dwordx2 v[12:13], v[10:11], off
	v_mul_f32_e32 v10, 0xbfb8aa3b, v6
	v_mul_f32_e32 v11, 0xbfb8aa3b, v7
	v_exp_f32_e32 v10, v10
	v_exp_f32_e32 v11, v11
	v_add_f32_e32 v10, 1.0, v10
	v_add_f32_e32 v11, 1.0, v11
	v_rcp_f32_e32 v10, v10
	v_rcp_f32_e32 v11, v11
	s_nop 0
	v_pk_mul_f32 v[6:7], v[6:7], v[10:11]
	s_nop 0
	v_pk_mul_f32 v[2:3], v[6:7], v[2:3]
	s_nop 0
	v_cvt_pk_bf16_f32 v2, v2, v3
	v_mul_f32_e32 v3, 0xbfb8aa3b, v8
	v_exp_f32_e32 v3, v3
	s_nop 0
	v_add_f32_e32 v3, 1.0, v3
	v_rcp_f32_e32 v6, v3
	v_mul_f32_e32 v3, 0xbfb8aa3b, v9
	v_exp_f32_e32 v3, v3
	s_nop 0
	v_add_f32_e32 v3, 1.0, v3
	v_rcp_f32_e32 v7, v3
	s_nop 0
	v_pk_mul_f32 v[6:7], v[8:9], v[6:7]
	s_nop 0
	v_pk_mul_f32 v[4:5], v[6:7], v[4:5]
	s_nop 0
	v_cvt_pk_bf16_f32 v3, v4, v5
	global_store_dwordx2 v[12:13], v[2:3], off offset:32
	s_and_b64 vcc, exec, s[0:1]
	s_mov_b32 s8, s5
	s_mov_b32 s9, s6
	s_mov_b32 s7, s4
	s_cbranch_vccz .LBB0_43
	s_waitcnt vmcnt(0)
	s_movk_i32 s0, 0x100
	v_cmp_gt_u32_e32 vcc, s0, v239
	s_and_saveexec_b64 s[0:1], vcc
	s_cbranch_execz .LBB0_50
	s_barrier

.LBB0_132:
	v_or_b32_e32 v131, 0x10000, v167
	v_add_u32_e32 v136, 0x10400, v167
	v_add_u32_e32 v140, 0x10800, v167
	v_add_u32_e32 v144, 0x10c00, v167
	s_add_i32 s11, s10, 2
	ds_read_b128 v[132:135], v131
	ds_read_b128 v[136:139], v136
	ds_read_b128 v[140:143], v140
	ds_read_b128 v[144:147], v144
	s_cmp_lt_u32 s10, 30
	s_cselect_b32 s12, s8, s5
	s_cselect_b32 s13, s7, s6
	s_cselect_b32 s14, s9, 0
	s_lshl_b32 s13, s13, 11
	s_lshl_b32 s12, s12, 11
	s_or_b32 s15, s14, 64
	s_add_i32 s17, s12, s14
	s_or_b32 s18, s13, 0x40000
	s_add_i32 s16, s13, s14
	s_add_i32 s13, s15, s13
	s_add_i32 s12, s15, s12
	s_lshl_b32 s17, s17, 1
	s_add_i32 s19, s18, s14
	s_add_i32 s18, s18, s15
	s_addk_i32 s9, 0x80
	s_lshl_b32 s16, s16, 1
	s_lshl_b32 s14, s13, 1
	s_lshl_b32 s13, s12, 1
	s_lshl_b32 s15, s19, 1
	s_add_i32 s19, s17, 0x80000
	s_lshl_b32 s12, s18, 1
	s_cmp_gt_u32 s10, 29
	v_add_u32_e32 v148, 0xc000, v0
	v_add_u32_e32 v131, 0xfffc0000, v130
	v_readfirstlane_b32 s10, v148
	s_mov_b32 m0, s10
	ds_read_b128 v[170:173], v166
	ds_read_b128 v[174:177], v166 offset:1024
	ds_read_b128 v[180:183], v166 offset:2048
	ds_read_b128 v[184:187], v166 offset:3072
	ds_read_b128 v[188:191], v166 offset:4096
	ds_read_b128 v[192:195], v166 offset:5120
	ds_read_b128 v[196:199], v166 offset:6144
	ds_read_b128 v[200:203], v166 offset:7168
	global_load_lds_dwordx4 v131, s[86:87]
	v_add_u32_e32 v131, 0xe000, v0
	s_nop 0
	v_readfirstlane_b32 s10, v131
	s_mov_b32 m0, s10
	s_nop 0
	global_load_lds_dwordx4 v130, s[86:87]
	s_waitcnt lgkmcnt(8)
	v_or_b32_e32 v131, 0x14000, v167
	v_add_u32_e32 v148, 0x14400, v167
	ds_read_b128 v[204:207], v131
	ds_read_b128 v[208:211], v148
	v_add_u32_e32 v131, 0x14800, v167
	v_add_u32_e32 v148, 0x14c00, v167
	ds_read_b128 v[212:215], v131
	ds_read_b128 v[216:219], v148
	s_waitcnt vmcnt(8)
	s_waitcnt lgkmcnt(0)
	s_barrier
	v_mfma_f32_16x16x32_bf16 v[98:101], v[132:135], v[170:173], v[98:101]
	v_mfma_f32_16x16x32_bf16 v[102:105], v[140:143], v[170:173], v[102:105]
	v_mfma_f32_16x16x32_bf16 v[126:129], v[132:135], v[180:183], v[126:129]
	v_mfma_f32_16x16x32_bf16 v[122:125], v[140:143], v[180:183], v[122:125]
	v_mfma_f32_16x16x32_bf16 v[118:121], v[132:135], v[188:191], v[118:121]
	v_mfma_f32_16x16x32_bf16 v[114:117], v[140:143], v[188:191], v[114:117]
	v_mfma_f32_16x16x32_bf16 v[110:113], v[132:135], v[196:199], v[110:113]
	v_mfma_f32_16x16x32_bf16 v[106:109], v[140:143], v[196:199], v[106:109]
	v_mfma_f32_16x16x32_bf16 v[98:101], v[136:139], v[174:177], v[98:101]
	v_mfma_f32_16x16x32_bf16 v[102:105], v[144:147], v[174:177], v[102:105]
	v_mfma_f32_16x16x32_bf16 v[126:129], v[136:139], v[184:187], v[126:129]
	v_mfma_f32_16x16x32_bf16 v[122:125], v[144:147], v[184:187], v[122:125]
	v_mfma_f32_16x16x32_bf16 v[118:121], v[136:139], v[192:195], v[118:121]
	v_mfma_f32_16x16x32_bf16 v[114:117], v[144:147], v[192:195], v[114:117]
	v_mfma_f32_16x16x32_bf16 v[110:113], v[136:139], v[200:203], v[110:113]
	v_mfma_f32_16x16x32_bf16 v[106:109], v[144:147], v[200:203], v[106:109]
	v_mfma_f32_16x16x32_bf16 v[66:69], v[204:207], v[170:173], v[66:69]
	v_mfma_f32_16x16x32_bf16 v[70:73], v[212:215], v[170:173], v[70:73]
	v_mfma_f32_16x16x32_bf16 v[74:77], v[204:207], v[180:183], v[74:77]
	v_mfma_f32_16x16x32_bf16 v[78:81], v[212:215], v[180:183], v[78:81]
	v_mfma_f32_16x16x32_bf16 v[82:85], v[204:207], v[188:191], v[82:85]
	v_mfma_f32_16x16x32_bf16 v[86:89], v[212:215], v[188:191], v[86:89]
	v_mfma_f32_16x16x32_bf16 v[90:93], v[204:207], v[196:199], v[90:93]
	v_mfma_f32_16x16x32_bf16 v[94:97], v[212:215], v[196:199], v[94:97]
	v_mfma_f32_16x16x32_bf16 v[66:69], v[208:211], v[174:177], v[66:69]
	v_mfma_f32_16x16x32_bf16 v[70:73], v[216:219], v[174:177], v[70:73]
	v_mfma_f32_16x16x32_bf16 v[74:77], v[208:211], v[184:187], v[74:77]
	v_mfma_f32_16x16x32_bf16 v[78:81], v[216:219], v[184:187], v[78:81]
	v_mfma_f32_16x16x32_bf16 v[82:85], v[208:211], v[192:195], v[82:85]
	v_mfma_f32_16x16x32_bf16 v[86:89], v[216:219], v[192:195], v[86:89]
	v_mfma_f32_16x16x32_bf16 v[90:93], v[208:211], v[200:203], v[90:93]
	v_mfma_f32_16x16x32_bf16 v[94:97], v[216:219], v[200:203], v[94:97]
	s_barrier
	v_readfirstlane_b32 s10, v152
	v_add_u32_e32 v131, s16, v150
	s_mov_b32 m0, s10
	v_readfirstlane_b32 s10, v153
	global_load_lds_dwordx4 v131, s[88:89]
	v_add_u32_e32 v131, s16, v151
	s_mov_b32 m0, s10
	s_nop 0
	global_load_lds_dwordx4 v131, s[88:89]
	v_readfirstlane_b32 s10, v0
	v_add_u32_e32 v131, s17, v150
	s_mov_b32 m0, s10
	v_readfirstlane_b32 s10, v154
	ds_read_b128 v[170:173], v166 offset:16384
	ds_read_b128 v[174:177], v166 offset:17408
	ds_read_b128 v[180:183], v166 offset:18432
	ds_read_b128 v[184:187], v166 offset:19456
	ds_read_b128 v[188:191], v166 offset:20480
	ds_read_b128 v[192:195], v166 offset:21504
	ds_read_b128 v[196:199], v166 offset:22528
	ds_read_b128 v[200:203], v166 offset:23552
	global_load_lds_dwordx4 v131, s[86:87]
	v_add_u32_e32 v131, s17, v151
	s_mov_b32 m0, s10
	s_nop 0
	global_load_lds_dwordx4 v131, s[86:87]
	v_readfirstlane_b32 s10, v155
	v_add_u32_e32 v131, s15, v150
	s_mov_b32 m0, s10
	v_readfirstlane_b32 s10, v156
	global_load_lds_dwordx4 v131, s[88:89]
	v_add_u32_e32 v131, s15, v151
	s_mov_b32 m0, s10
	s_nop 0
	global_load_lds_dwordx4 v131, s[88:89]
	s_waitcnt vmcnt(8)
	s_waitcnt lgkmcnt(0)
	s_barrier
	v_mfma_f32_16x16x32_bf16 v[34:37], v[132:135], v[170:173], v[34:37]
	v_mfma_f32_16x16x32_bf16 v[38:41], v[140:143], v[170:173], v[38:41]
	v_mfma_f32_16x16x32_bf16 v[42:45], v[132:135], v[180:183], v[42:45]
	v_mfma_f32_16x16x32_bf16 v[46:49], v[140:143], v[180:183], v[46:49]
	v_mfma_f32_16x16x32_bf16 v[50:53], v[132:135], v[188:191], v[50:53]
	v_mfma_f32_16x16x32_bf16 v[54:57], v[140:143], v[188:191], v[54:57]
	v_mfma_f32_16x16x32_bf16 v[58:61], v[132:135], v[196:199], v[58:61]
	v_mfma_f32_16x16x32_bf16 v[62:65], v[140:143], v[196:199], v[62:65]
	v_mfma_f32_16x16x32_bf16 v[34:37], v[136:139], v[174:177], v[34:37]
	v_mfma_f32_16x16x32_bf16 v[38:41], v[144:147], v[174:177], v[38:41]
	v_mfma_f32_16x16x32_bf16 v[42:45], v[136:139], v[184:187], v[42:45]
	v_mfma_f32_16x16x32_bf16 v[46:49], v[144:147], v[184:187], v[46:49]
	v_mfma_f32_16x16x32_bf16 v[50:53], v[136:139], v[192:195], v[50:53]
	v_mfma_f32_16x16x32_bf16 v[54:57], v[144:147], v[192:195], v[54:57]
	v_mfma_f32_16x16x32_bf16 v[58:61], v[136:139], v[200:203], v[58:61]
	v_mfma_f32_16x16x32_bf16 v[62:65], v[144:147], v[200:203], v[62:65]
	v_mfma_f32_16x16x32_bf16 v[2:5], v[204:207], v[170:173], v[2:5]
	v_mfma_f32_16x16x32_bf16 v[6:9], v[212:215], v[170:173], v[6:9]
	v_mfma_f32_16x16x32_bf16 v[10:13], v[204:207], v[180:183], v[10:13]
	v_mfma_f32_16x16x32_bf16 v[14:17], v[212:215], v[180:183], v[14:17]
	v_mfma_f32_16x16x32_bf16 v[18:21], v[204:207], v[188:191], v[18:21]
	v_mfma_f32_16x16x32_bf16 v[22:25], v[212:215], v[188:191], v[22:25]
	v_mfma_f32_16x16x32_bf16 v[26:29], v[204:207], v[196:199], v[26:29]
	v_mfma_f32_16x16x32_bf16 v[30:33], v[212:215], v[196:199], v[30:33]
	v_mfma_f32_16x16x32_bf16 v[2:5], v[208:211], v[174:177], v[2:5]
	v_mfma_f32_16x16x32_bf16 v[6:9], v[216:219], v[174:177], v[6:9]
	v_mfma_f32_16x16x32_bf16 v[10:13], v[208:211], v[184:187], v[10:13]
	v_mfma_f32_16x16x32_bf16 v[14:17], v[216:219], v[184:187], v[14:17]
	v_mfma_f32_16x16x32_bf16 v[18:21], v[208:211], v[192:195], v[18:21]
	v_mfma_f32_16x16x32_bf16 v[22:25], v[216:219], v[192:195], v[22:25]
	v_mfma_f32_16x16x32_bf16 v[26:29], v[208:211], v[200:203], v[26:29]
	v_mfma_f32_16x16x32_bf16 v[30:33], v[216:219], v[200:203], v[30:33]
	s_barrier
	v_or_b32_e32 v131, 0x18000, v167
	v_add_u32_e32 v136, 0x18400, v167
	ds_read_b128 v[132:135], v131
	ds_read_b128 v[136:139], v136
	v_add_u32_e32 v131, 0x18800, v167
	v_add_u32_e32 v144, 0x18c00, v167
	ds_read_b128 v[140:143], v131
	ds_read_b128 v[144:147], v144
	v_readfirstlane_b32 s10, v157
	v_add_u32_e32 v131, s19, v150
	s_mov_b32 m0, s10
	v_readfirstlane_b32 s10, v158
	ds_read_b128 v[170:173], v166 offset:32768
	ds_read_b128 v[174:177], v166 offset:33792
	ds_read_b128 v[180:183], v166 offset:34816
	ds_read_b128 v[184:187], v166 offset:35840
	ds_read_b128 v[188:191], v166 offset:36864
	ds_read_b128 v[192:195], v166 offset:37888
	ds_read_b128 v[196:199], v166 offset:38912
	ds_read_b128 v[200:203], v166 offset:39936
	global_load_lds_dwordx4 v131, s[86:87]
	v_add_u32_e32 v131, s19, v151
	s_mov_b32 m0, s10
	s_nop 0
	global_load_lds_dwordx4 v131, s[86:87]
	s_waitcnt lgkmcnt(8)
	v_or_b32_e32 v131, 0x1c000, v167
	v_add_u32_e32 v148, 0x1c400, v167
	ds_read_b128 v[204:207], v131
	ds_read_b128 v[208:211], v148
	v_add_u32_e32 v131, 0x1c800, v167
	v_add_u32_e32 v148, 0x1cc00, v167
	ds_read_b128 v[212:215], v131
	ds_read_b128 v[216:219], v148
	s_waitcnt vmcnt(8)
	s_waitcnt lgkmcnt(0)
	s_barrier
	v_mfma_f32_16x16x32_bf16 v[98:101], v[132:135], v[170:173], v[98:101]
	v_mfma_f32_16x16x32_bf16 v[102:105], v[140:143], v[170:173], v[102:105]
	v_mfma_f32_16x16x32_bf16 v[126:129], v[132:135], v[180:183], v[126:129]
	v_mfma_f32_16x16x32_bf16 v[122:125], v[140:143], v[180:183], v[122:125]
	v_mfma_f32_16x16x32_bf16 v[118:121], v[132:135], v[188:191], v[118:121]
	v_mfma_f32_16x16x32_bf16 v[114:117], v[140:143], v[188:191], v[114:117]
	v_mfma_f32_16x16x32_bf16 v[110:113], v[132:135], v[196:199], v[110:113]
	v_mfma_f32_16x16x32_bf16 v[106:109], v[140:143], v[196:199], v[106:109]
	v_mfma_f32_16x16x32_bf16 v[98:101], v[136:139], v[174:177], v[98:101]
	v_mfma_f32_16x16x32_bf16 v[102:105], v[144:147], v[174:177], v[102:105]
	v_mfma_f32_16x16x32_bf16 v[126:129], v[136:139], v[184:187], v[126:129]
	v_mfma_f32_16x16x32_bf16 v[122:125], v[144:147], v[184:187], v[122:125]
	v_mfma_f32_16x16x32_bf16 v[118:121], v[136:139], v[192:195], v[118:121]
	v_mfma_f32_16x16x32_bf16 v[114:117], v[144:147], v[192:195], v[114:117]
	v_mfma_f32_16x16x32_bf16 v[110:113], v[136:139], v[200:203], v[110:113]
	v_mfma_f32_16x16x32_bf16 v[106:109], v[144:147], v[200:203], v[106:109]
	v_mfma_f32_16x16x32_bf16 v[66:69], v[204:207], v[170:173], v[66:69]
	v_mfma_f32_16x16x32_bf16 v[70:73], v[212:215], v[170:173], v[70:73]
	v_mfma_f32_16x16x32_bf16 v[74:77], v[204:207], v[180:183], v[74:77]
	v_mfma_f32_16x16x32_bf16 v[78:81], v[212:215], v[180:183], v[78:81]
	v_mfma_f32_16x16x32_bf16 v[82:85], v[204:207], v[188:191], v[82:85]
	v_mfma_f32_16x16x32_bf16 v[86:89], v[212:215], v[188:191], v[86:89]
	v_mfma_f32_16x16x32_bf16 v[90:93], v[204:207], v[196:199], v[90:93]
	v_mfma_f32_16x16x32_bf16 v[94:97], v[212:215], v[196:199], v[94:97]
	v_mfma_f32_16x16x32_bf16 v[66:69], v[208:211], v[174:177], v[66:69]
	v_mfma_f32_16x16x32_bf16 v[70:73], v[216:219], v[174:177], v[70:73]
	v_mfma_f32_16x16x32_bf16 v[74:77], v[208:211], v[184:187], v[74:77]
	v_mfma_f32_16x16x32_bf16 v[78:81], v[216:219], v[184:187], v[78:81]
	v_mfma_f32_16x16x32_bf16 v[82:85], v[208:211], v[192:195], v[82:85]
	v_mfma_f32_16x16x32_bf16 v[86:89], v[216:219], v[192:195], v[86:89]
	v_mfma_f32_16x16x32_bf16 v[90:93], v[208:211], v[200:203], v[90:93]
	v_mfma_f32_16x16x32_bf16 v[94:97], v[216:219], v[200:203], v[94:97]
	s_barrier
; DI void gemm_resid(const u16* A, const u16* Bt, int K, const float* xin, float* xout, int bid, int nb, int tid) {
;     ...
; #pragma unroll
;     for (int ai = 0; ai < 2; ++ai)
; #pragma unroll
;       for (int bj = 0; bj < 2; ++bj) {
;         float4 xi[4][2];
; #pragma unroll
;         for (int m = 0; m < 4; ++m)
; #pragma unroll
;           for (int n = 0; n < 2; ++n) xi[m][n] = *reinterpret_cast<const float4*>(xin + (size_t)ACC_ROW * 2048 + ACC_COL);
	v_readfirstlane_b32 s10, v159
	v_add_u32_e32 v131, s14, v150
	s_mov_b32 m0, s10
	v_readfirstlane_b32 s10, v160
	global_load_lds_dwordx4 v131, s[88:89]
	v_add_u32_e32 v131, s14, v151
	s_mov_b32 m0, s10
	s_nop 0
	global_load_lds_dwordx4 v131, s[88:89]
	v_readfirstlane_b32 s10, v161
	v_add_u32_e32 v131, s13, v150
	s_mov_b32 m0, s10
	v_readfirstlane_b32 s10, v162
	ds_read_b128 v[170:173], v166 offset:49152
	ds_read_b128 v[174:177], v166 offset:50176
	ds_read_b128 v[180:183], v166 offset:51200
	ds_read_b128 v[184:187], v166 offset:52224
	ds_read_b128 v[188:191], v166 offset:53248
	ds_read_b128 v[192:195], v166 offset:54272
	ds_read_b128 v[196:199], v166 offset:55296
	ds_read_b128 v[200:203], v166 offset:56320
	global_load_lds_dwordx4 v131, s[86:87]
	v_add_u32_e32 v131, s13, v151
	s_mov_b32 m0, s10
	s_nop 0
	global_load_lds_dwordx4 v131, s[86:87]
	v_readfirstlane_b32 s10, v163
	v_add_u32_e32 v131, s12, v150
	s_mov_b32 m0, s10
	v_readfirstlane_b32 s10, v165
	global_load_lds_dwordx4 v131, s[88:89]
	v_add_u32_e32 v131, s12, v151
	s_mov_b32 m0, s10
	s_nop 0
	global_load_lds_dwordx4 v131, s[88:89]
	s_waitcnt vmcnt(8)
	s_waitcnt lgkmcnt(0)
	s_barrier
	v_mfma_f32_16x16x32_bf16 v[34:37], v[132:135], v[170:173], v[34:37]
	v_mfma_f32_16x16x32_bf16 v[38:41], v[140:143], v[170:173], v[38:41]
	v_mfma_f32_16x16x32_bf16 v[42:45], v[132:135], v[180:183], v[42:45]
	v_mfma_f32_16x16x32_bf16 v[46:49], v[140:143], v[180:183], v[46:49]
	v_mfma_f32_16x16x32_bf16 v[50:53], v[132:135], v[188:191], v[50:53]
	v_mfma_f32_16x16x32_bf16 v[54:57], v[140:143], v[188:191], v[54:57]
	v_mfma_f32_16x16x32_bf16 v[58:61], v[132:135], v[196:199], v[58:61]
	v_mfma_f32_16x16x32_bf16 v[62:65], v[140:143], v[196:199], v[62:65]
	v_mfma_f32_16x16x32_bf16 v[34:37], v[136:139], v[174:177], v[34:37]
	v_mfma_f32_16x16x32_bf16 v[38:41], v[144:147], v[174:177], v[38:41]
	v_mfma_f32_16x16x32_bf16 v[42:45], v[136:139], v[184:187], v[42:45]
	v_mfma_f32_16x16x32_bf16 v[46:49], v[144:147], v[184:187], v[46:49]
	v_mfma_f32_16x16x32_bf16 v[50:53], v[136:139], v[192:195], v[50:53]
	v_mfma_f32_16x16x32_bf16 v[54:57], v[144:147], v[192:195], v[54:57]
	v_mfma_f32_16x16x32_bf16 v[58:61], v[136:139], v[200:203], v[58:61]
	v_mfma_f32_16x16x32_bf16 v[62:65], v[144:147], v[200:203], v[62:65]
	v_mfma_f32_16x16x32_bf16 v[2:5], v[204:207], v[170:173], v[2:5]
	v_mfma_f32_16x16x32_bf16 v[6:9], v[212:215], v[170:173], v[6:9]
	v_mfma_f32_16x16x32_bf16 v[10:13], v[204:207], v[180:183], v[10:13]
	v_mfma_f32_16x16x32_bf16 v[14:17], v[212:215], v[180:183], v[14:17]
	v_mfma_f32_16x16x32_bf16 v[18:21], v[204:207], v[188:191], v[18:21]
	v_mfma_f32_16x16x32_bf16 v[22:25], v[212:215], v[188:191], v[22:25]
	v_mfma_f32_16x16x32_bf16 v[26:29], v[204:207], v[196:199], v[26:29]
	v_mfma_f32_16x16x32_bf16 v[30:33], v[212:215], v[196:199], v[30:33]
	v_mfma_f32_16x16x32_bf16 v[2:5], v[208:211], v[174:177], v[2:5]
	v_mfma_f32_16x16x32_bf16 v[6:9], v[216:219], v[174:177], v[6:9]
	v_mfma_f32_16x16x32_bf16 v[10:13], v[208:211], v[184:187], v[10:13]
	v_mfma_f32_16x16x32_bf16 v[14:17], v[216:219], v[184:187], v[14:17]
	v_mfma_f32_16x16x32_bf16 v[18:21], v[208:211], v[192:195], v[18:21]
	v_mfma_f32_16x16x32_bf16 v[22:25], v[216:219], v[192:195], v[22:25]
	v_mfma_f32_16x16x32_bf16 v[26:29], v[208:211], v[200:203], v[26:29]
	v_mfma_f32_16x16x32_bf16 v[30:33], v[216:219], v[200:203], v[30:33]
	v_add_u32_e32 v130, 0x100, v130
	s_mov_b32 s10, s11
	s_barrier
	s_cbranch_scc0 .LBB0_132
	v_mov_b32_e32 v131, v239
	s_nop 0
	v_ashrrev_i32_e32 v130, 2, v131
	v_and_b32_e32 v130, 0xffffffc0, v130
	v_and_or_b32 v132, v131, 15, s8
	v_add_u32_e32 v130, v132, v130
	v_lshrrev_b32_e32 v132, 1, v131
	v_lshrrev_b32_e32 v131, 2, v131
	v_and_b32_e32 v132, 0x60, v132
	v_and_b32_e32 v131, 12, v131
	v_or3_b32 v132, v132, v131, s7
	v_ashrrev_i32_e32 v131, 31, v130
	v_ashrrev_i32_e32 v133, 31, v132
	v_lshlrev_b64 v[134:135], 13, v[130:131]
	v_lshl_add_u64 v[136:137], s[48:49], 0, v[134:135]
	v_lshlrev_b64 v[132:133], 2, v[132:133]
	v_lshl_add_u64 v[142:143], v[136:137], 0, v[132:133]
	v_or_b32_e32 v136, 16, v130
	v_ashrrev_i32_e32 v137, 31, v136
	v_lshlrev_b64 v[136:137], 13, v[136:137]
	v_lshl_add_u64 v[138:139], s[48:49], 0, v[136:137]
	v_lshl_add_u64 v[144:145], v[138:139], 0, v[132:133]
	v_or_b32_e32 v138, 32, v130
	v_ashrrev_i32_e32 v139, 31, v138
	v_lshlrev_b64 v[170:171], 13, v[138:139]
	v_lshl_add_u64 v[138:139], s[48:49], 0, v[170:171]
	v_lshl_add_u64 v[146:147], v[138:139], 0, v[132:133]
	v_or_b32_e32 v138, 48, v130
	v_ashrrev_i32_e32 v139, 31, v138
	v_lshlrev_b64 v[172:173], 13, v[138:139]
	v_lshl_add_u64 v[134:135], s[72:73], 0, v[134:135]
	v_lshl_add_u64 v[138:139], s[48:49], 0, v[172:173]
	v_lshl_add_u64 v[140:141], v[134:135], 0, v[132:133]
	v_lshl_add_u64 v[134:135], s[72:73], 0, v[136:137]
	v_lshl_add_u64 v[148:149], v[138:139], 0, v[132:133]
	v_lshl_add_u64 v[138:139], v[134:135], 0, v[132:133]
	v_lshl_add_u64 v[134:135], s[72:73], 0, v[170:171]
	v_lshl_add_u64 v[136:137], v[134:135], 0, v[132:133]
	v_lshl_add_u64 v[134:135], s[72:73], 0, v[172:173]
	v_lshl_add_u64 v[134:135], v[134:135], 0, v[132:133]
	global_load_dwordx4 v[180:183], v[148:149], off offset:64
	global_load_dwordx4 v[184:187], v[148:149], off
	global_load_dwordx4 v[188:191], v[146:147], off offset:64
	global_load_dwordx4 v[192:195], v[146:147], off
	global_load_dwordx4 v[196:199], v[144:145], off offset:64
	global_load_dwordx4 v[200:203], v[144:145], off
	global_load_dwordx4 v[204:207], v[142:143], off offset:64
	global_load_dwordx4 v[208:211], v[142:143], off
	s_waitcnt vmcnt(0)
; #define EPI_SCHED __builtin_amdgcn_sched_barrier(0)
; DI void gemm_resid(const u16* A, const u16* Bt, int K, const float* xin, float* xout, int bid, int nb, int tid) {
;     ...
; #pragma unroll
;     for (int ai = 0; ai < 2; ++ai)
; #pragma unroll
;       for (int bj = 0; bj < 2; ++bj) {
;         float4 xi[4][2];
; #pragma unroll
;         for (int m = 0; m < 4; ++m)
; #pragma unroll
;           for (int n = 0; n < 2; ++n) xi[m][n] = *reinterpret_cast<const float4*>(xin + (size_t)ACC_ROW * 2048 + ACC_COL);
; #pragma unroll
;         for (int m = 0; m < 4; ++m)
; #pragma unroll
;           for (int n = 0; n < 2; ++n) {
;             const f32x4 v = acc[ai][bj][m][n];
;             float4 r; r.x = xi[m][n].x + v[0]; r.y = xi[m][n].y + v[1]; r.z = xi[m][n].z + v[2]; r.w = xi[m][n].w + v[3];
;             *reinterpret_cast<float4*>(xout + (size_t)ACC_ROW * 2048 + ACC_COL) = r;
;           }
;         EPI_SCHED;
;       }
	v_pk_add_f32 v[106:107], v[106:107], v[180:181]
	v_pk_add_f32 v[108:109], v[108:109], v[182:183]
	v_pk_add_f32 v[110:111], v[110:111], v[184:185]
	v_pk_add_f32 v[112:113], v[112:113], v[186:187]
	v_pk_add_f32 v[114:115], v[114:115], v[188:189]
	v_pk_add_f32 v[116:117], v[116:117], v[190:191]
	v_pk_add_f32 v[118:119], v[118:119], v[192:193]
	v_pk_add_f32 v[120:121], v[120:121], v[194:195]
	v_pk_add_f32 v[122:123], v[122:123], v[196:197]
	v_pk_add_f32 v[124:125], v[124:125], v[198:199]
	v_pk_add_f32 v[126:127], v[126:127], v[200:201]
	v_pk_add_f32 v[128:129], v[128:129], v[202:203]
	v_pk_add_f32 v[102:103], v[102:103], v[204:205]
	v_pk_add_f32 v[104:105], v[104:105], v[206:207]
	v_pk_add_f32 v[98:99], v[98:99], v[208:209]
	v_pk_add_f32 v[100:101], v[100:101], v[210:211]
	global_store_dwordx4 v[140:141], v[98:101], off
	global_store_dwordx4 v[140:141], v[102:105], off offset:64
	global_store_dwordx4 v[138:139], v[126:129], off
	global_store_dwordx4 v[138:139], v[122:125], off offset:64
	global_store_dwordx4 v[136:137], v[118:121], off
	global_store_dwordx4 v[136:137], v[114:117], off offset:64
	global_store_dwordx4 v[134:135], v[110:113], off
	global_store_dwordx4 v[134:135], v[106:109], off offset:64
	global_load_dwordx4 v[180:183], v[148:149], off offset:576
	global_load_dwordx4 v[184:187], v[148:149], off offset:512
	global_load_dwordx4 v[188:191], v[146:147], off offset:576
	global_load_dwordx4 v[192:195], v[146:147], off offset:512
	global_load_dwordx4 v[196:199], v[144:145], off offset:576
	global_load_dwordx4 v[200:203], v[144:145], off offset:512
	global_load_dwordx4 v[204:207], v[142:143], off offset:576
	global_load_dwordx4 v[208:211], v[142:143], off offset:512
	s_waitcnt vmcnt(0)
	v_pk_add_f32 v[94:95], v[94:95], v[180:181]
	v_pk_add_f32 v[96:97], v[96:97], v[182:183]
	v_pk_add_f32 v[90:91], v[90:91], v[184:185]
	v_pk_add_f32 v[92:93], v[92:93], v[186:187]
	v_pk_add_f32 v[86:87], v[86:87], v[188:189]
	v_pk_add_f32 v[88:89], v[88:89], v[190:191]
	v_pk_add_f32 v[82:83], v[82:83], v[192:193]
	v_pk_add_f32 v[84:85], v[84:85], v[194:195]
	v_pk_add_f32 v[78:79], v[78:79], v[196:197]
	v_pk_add_f32 v[80:81], v[80:81], v[198:199]
	v_pk_add_f32 v[74:75], v[74:75], v[200:201]
	v_pk_add_f32 v[76:77], v[76:77], v[202:203]
	v_pk_add_f32 v[70:71], v[70:71], v[204:205]
	v_pk_add_f32 v[72:73], v[72:73], v[206:207]
	v_pk_add_f32 v[66:67], v[66:67], v[208:209]
	v_pk_add_f32 v[68:69], v[68:69], v[210:211]
	global_store_dwordx4 v[140:141], v[66:69], off offset:512
	global_store_dwordx4 v[140:141], v[70:73], off offset:576
	global_store_dwordx4 v[138:139], v[74:77], off offset:512
	global_store_dwordx4 v[138:139], v[78:81], off offset:576
	global_store_dwordx4 v[136:137], v[82:85], off offset:512
	global_store_dwordx4 v[136:137], v[86:89], off offset:576
	global_store_dwordx4 v[134:135], v[90:93], off offset:512
	global_store_dwordx4 v[134:135], v[94:97], off offset:576
	v_add_u32_e32 v66, 0x80, v130
	v_ashrrev_i32_e32 v67, 31, v66
	v_lshlrev_b64 v[66:67], 13, v[66:67]
	v_lshl_add_u64 v[68:69], s[48:49], 0, v[66:67]
	v_lshl_add_u64 v[74:75], v[68:69], 0, v[132:133]
	v_add_u32_e32 v68, 0x90, v130
	v_ashrrev_i32_e32 v69, 31, v68
	v_lshlrev_b64 v[68:69], 13, v[68:69]
	v_lshl_add_u64 v[70:71], s[48:49], 0, v[68:69]
	v_lshl_add_u64 v[76:77], v[70:71], 0, v[132:133]
	v_add_u32_e32 v70, 0xa0, v130
	v_ashrrev_i32_e32 v71, 31, v70
	v_lshlrev_b64 v[82:83], 13, v[70:71]
	v_lshl_add_u64 v[70:71], s[48:49], 0, v[82:83]
	v_lshl_add_u64 v[78:79], v[70:71], 0, v[132:133]
	v_add_u32_e32 v70, 0xb0, v130
	v_ashrrev_i32_e32 v71, 31, v70
	v_lshlrev_b64 v[84:85], 13, v[70:71]
	v_lshl_add_u64 v[66:67], s[72:73], 0, v[66:67]
	v_lshl_add_u64 v[70:71], s[48:49], 0, v[84:85]
	v_lshl_add_u64 v[72:73], v[66:67], 0, v[132:133]
	v_lshl_add_u64 v[66:67], s[72:73], 0, v[68:69]
	v_lshl_add_u64 v[80:81], v[70:71], 0, v[132:133]
	v_lshl_add_u64 v[70:71], v[66:67], 0, v[132:133]
	v_lshl_add_u64 v[66:67], s[72:73], 0, v[82:83]
	v_lshl_add_u64 v[68:69], v[66:67], 0, v[132:133]
	v_lshl_add_u64 v[66:67], s[72:73], 0, v[84:85]
	v_lshl_add_u64 v[66:67], v[66:67], 0, v[132:133]
	global_load_dwordx4 v[180:183], v[80:81], off offset:64
	global_load_dwordx4 v[184:187], v[80:81], off
	global_load_dwordx4 v[188:191], v[78:79], off offset:64
	global_load_dwordx4 v[192:195], v[78:79], off
	global_load_dwordx4 v[196:199], v[76:77], off offset:64
	global_load_dwordx4 v[200:203], v[76:77], off
	global_load_dwordx4 v[204:207], v[74:75], off offset:64
	global_load_dwordx4 v[208:211], v[74:75], off
	s_waitcnt vmcnt(0)
; #define WAIT_V(n) asm volatile("s_waitcnt vmcnt(" #n ")" ::: "memory")
; #define BAR __builtin_amdgcn_s_barrier()
; #define EPI_SCHED __builtin_amdgcn_sched_barrier(0)
; template <class EPI>
; DI void gemm_stream(const u16* __restrict__ A, const u16* __restrict__ Bt, const int K, const int nM, const int nN,
;                     const int bid, const int nb, const int tid, EPI epi) {
;     ...
;   WAIT_V(0);
;   if (wr == 0) BAR;
;   BAR;
; DI void gemm_resid(const u16* A, const u16* Bt, int K, const float* xin, float* xout, int bid, int nb, int tid) {
;     ...
; #pragma unroll
;     for (int ai = 0; ai < 2; ++ai)
; #pragma unroll
;       for (int bj = 0; bj < 2; ++bj) {
;         float4 xi[4][2];
; #pragma unroll
;         for (int m = 0; m < 4; ++m)
; #pragma unroll
;           for (int n = 0; n < 2; ++n) xi[m][n] = *reinterpret_cast<const float4*>(xin + (size_t)ACC_ROW * 2048 + ACC_COL);
; #pragma unroll
;         for (int m = 0; m < 4; ++m)
; #pragma unroll
;           for (int n = 0; n < 2; ++n) {
;             const f32x4 v = acc[ai][bj][m][n];
;             float4 r; r.x = xi[m][n].x + v[0]; r.y = xi[m][n].y + v[1]; r.z = xi[m][n].z + v[2]; r.w = xi[m][n].w + v[3];
;             *reinterpret_cast<float4*>(xout + (size_t)ACC_ROW * 2048 + ACC_COL) = r;
;           }
;         EPI_SCHED;
;       }
	v_pk_add_f32 v[62:63], v[62:63], v[180:181]
	v_pk_add_f32 v[64:65], v[64:65], v[182:183]
	v_pk_add_f32 v[58:59], v[58:59], v[184:185]
	v_pk_add_f32 v[60:61], v[60:61], v[186:187]
	v_pk_add_f32 v[54:55], v[54:55], v[188:189]
	v_pk_add_f32 v[56:57], v[56:57], v[190:191]
	v_pk_add_f32 v[50:51], v[50:51], v[192:193]
	v_pk_add_f32 v[52:53], v[52:53], v[194:195]
	v_pk_add_f32 v[46:47], v[46:47], v[196:197]
	v_pk_add_f32 v[48:49], v[48:49], v[198:199]
	v_pk_add_f32 v[42:43], v[42:43], v[200:201]
	v_pk_add_f32 v[44:45], v[44:45], v[202:203]
	v_pk_add_f32 v[38:39], v[38:39], v[204:205]
	v_pk_add_f32 v[40:41], v[40:41], v[206:207]
	v_pk_add_f32 v[34:35], v[34:35], v[208:209]
	v_pk_add_f32 v[36:37], v[36:37], v[210:211]
	global_store_dwordx4 v[72:73], v[34:37], off
	global_store_dwordx4 v[72:73], v[38:41], off offset:64
	global_store_dwordx4 v[70:71], v[42:45], off
	global_store_dwordx4 v[70:71], v[46:49], off offset:64
	global_store_dwordx4 v[68:69], v[50:53], off
	global_store_dwordx4 v[68:69], v[54:57], off offset:64
	global_store_dwordx4 v[66:67], v[58:61], off
	global_store_dwordx4 v[66:67], v[62:65], off offset:64
	global_load_dwordx4 v[180:183], v[80:81], off offset:576
	global_load_dwordx4 v[184:187], v[80:81], off offset:512
	global_load_dwordx4 v[188:191], v[78:79], off offset:576
	global_load_dwordx4 v[192:195], v[78:79], off offset:512
	global_load_dwordx4 v[196:199], v[76:77], off offset:576
	global_load_dwordx4 v[200:203], v[76:77], off offset:512
	global_load_dwordx4 v[204:207], v[74:75], off offset:576
	global_load_dwordx4 v[208:211], v[74:75], off offset:512
	s_waitcnt vmcnt(0)
	v_pk_add_f32 v[30:31], v[30:31], v[180:181]
	v_pk_add_f32 v[32:33], v[32:33], v[182:183]
	v_pk_add_f32 v[26:27], v[26:27], v[184:185]
	v_pk_add_f32 v[28:29], v[28:29], v[186:187]
	v_pk_add_f32 v[22:23], v[22:23], v[188:189]
	v_pk_add_f32 v[24:25], v[24:25], v[190:191]
	v_pk_add_f32 v[18:19], v[18:19], v[192:193]
	v_pk_add_f32 v[20:21], v[20:21], v[194:195]
	v_pk_add_f32 v[14:15], v[14:15], v[196:197]
	v_pk_add_f32 v[16:17], v[16:17], v[198:199]
	v_pk_add_f32 v[10:11], v[10:11], v[200:201]
	v_pk_add_f32 v[12:13], v[12:13], v[202:203]
	v_pk_add_f32 v[6:7], v[6:7], v[204:205]
	v_pk_add_f32 v[8:9], v[8:9], v[206:207]
	v_pk_add_f32 v[2:3], v[2:3], v[208:209]
	v_pk_add_f32 v[4:5], v[4:5], v[210:211]
	global_store_dwordx4 v[72:73], v[2:5], off offset:512
	global_store_dwordx4 v[72:73], v[6:9], off offset:576
	global_store_dwordx4 v[70:71], v[10:13], off offset:512
	global_store_dwordx4 v[70:71], v[14:17], off offset:576
	global_store_dwordx4 v[68:69], v[18:21], off offset:512
	global_store_dwordx4 v[68:69], v[22:25], off offset:576
	global_store_dwordx4 v[66:67], v[26:29], off offset:512
	global_store_dwordx4 v[66:67], v[30:33], off offset:576
	s_and_b64 vcc, exec, s[0:1]
	s_mov_b32 s8, s5
	s_mov_b32 s7, s6
	s_cbranch_vccz .LBB0_129
	s_waitcnt vmcnt(0)
	s_movk_i32 s0, 0x100
	v_cmp_gt_u32_e32 vcc, s0, v239
	s_and_saveexec_b64 s[0:1], vcc
	s_cbranch_execz .LBB0_136
	s_barrier

.Lpj48_loop:
	v_or_b32_e32 v122, 0x10000, v200
	v_add_u32_e32 v134, 0x10400, v200
	v_add_u32_e32 v138, 0x10800, v200
	v_add_u32_e32 v142, 0x10c00, v200
	ds_read_b128 v[122:125], v122
	ds_read_b128 v[134:137], v134
	ds_read_b128 v[138:141], v138
	ds_read_b128 v[142:145], v142
	s_add_i32 s1, s0, -2
	s_cmp_lt_u32 s1, 30
	s_cselect_b32 s3, s4, s16
	s_cselect_b32 s5, s2, s15
	v_add_u32_e32 v181, 0xc000, v179
	v_add_u32_e32 v180, 0xfffc0000, v0
	v_readfirstlane_b32 s6, v181
	s_mov_b32 m0, s6
	ds_read_b128 v[146:149], v199
	ds_read_b128 v[150:153], v199 offset:1024
	ds_read_b128 v[154:157], v199 offset:2048
	ds_read_b128 v[158:161], v199 offset:3072
	ds_read_b128 v[162:165], v199 offset:4096
	ds_read_b128 v[166:169], v199 offset:5120
	ds_read_b128 v[170:173], v199 offset:6144
	ds_read_b128 v[174:177], v199 offset:7168
	global_load_lds_dwordx4 v180, s[80:81]
	v_add_u32_e32 v180, 0xe000, v179
	s_nop 0
	v_readfirstlane_b32 s6, v180
	s_mov_b32 m0, s6
	s_nop 0
	global_load_lds_dwordx4 v0, s[80:81]
	s_waitcnt lgkmcnt(8)
	v_or_b32_e32 v180, 0x14000, v200
	v_add_u32_e32 v202, 0x14400, v200
	v_add_u32_e32 v206, 0x14800, v200
	v_add_u32_e32 v210, 0x14c00, v200
	ds_read_b128 v[180:183], v180
	ds_read_b128 v[202:205], v202
	ds_read_b128 v[206:209], v206
	ds_read_b128 v[210:213], v210
	s_waitcnt vmcnt(8)
	s_waitcnt lgkmcnt(0)
	s_barrier
	v_mfma_f32_16x16x32_bf16 v[130:133], v[122:125], v[146:149], v[130:133]
	v_mfma_f32_16x16x32_bf16 v[110:113], v[122:125], v[154:157], v[110:113]
	v_mfma_f32_16x16x32_bf16 v[94:97], v[122:125], v[162:165], v[94:97]
	v_mfma_f32_16x16x32_bf16 v[78:81], v[122:125], v[170:173], v[78:81]
	v_mfma_f32_16x16x32_bf16 v[130:133], v[134:137], v[150:153], v[130:133]
	v_mfma_f32_16x16x32_bf16 v[110:113], v[134:137], v[158:161], v[110:113]
	v_mfma_f32_16x16x32_bf16 v[94:97], v[134:137], v[166:169], v[94:97]
	v_mfma_f32_16x16x32_bf16 v[78:81], v[134:137], v[174:177], v[78:81]
	s_barrier
	s_cselect_b32 s6, s0, 0
	s_lshl_b32 s3, s3, 11
	s_lshl_b32 s7, s6, 6
	s_or_b32 s10, s3, s7
	s_lshl_b32 s10, s10, 1
	v_readfirstlane_b32 s11, v186
	v_add_u32_e32 v214, s10, v184
	s_mov_b32 m0, s11
	global_load_lds_dwordx4 v214, s[74:75]
	v_add_u32_e32 v214, s10, v185
	v_readfirstlane_b32 s10, v187
	s_mov_b32 m0, s10
	s_nop 0
	global_load_lds_dwordx4 v214, s[74:75]
	s_lshl_b32 s10, s5, 11
	s_or_b32 s11, s10, s7
	s_lshl_b32 s11, s11, 1
	v_readfirstlane_b32 s18, v179
	v_add_u32_e32 v214, s11, v184
	s_mov_b32 m0, s18
	ds_read_b128 v[146:149], v199 offset:16384
	ds_read_b128 v[150:153], v199 offset:17408
	ds_read_b128 v[154:157], v199 offset:18432
	ds_read_b128 v[158:161], v199 offset:19456
	ds_read_b128 v[162:165], v199 offset:20480
	ds_read_b128 v[166:169], v199 offset:21504
	ds_read_b128 v[170:173], v199 offset:22528
	ds_read_b128 v[174:177], v199 offset:23552
	global_load_lds_dwordx4 v214, s[80:81]
	v_add_u32_e32 v214, s11, v185
	v_readfirstlane_b32 s11, v188
	s_mov_b32 m0, s11
	s_nop 0
	global_load_lds_dwordx4 v214, s[80:81]
	s_or_b32 s11, s3, 0x40000
	s_or_b32 s18, s11, s7
	s_lshl_b32 s18, s18, 1
	v_readfirstlane_b32 s19, v189
	v_add_u32_e32 v215, s18, v184
	s_mov_b32 m0, s19
	s_nop 0
	global_load_lds_dwordx4 v215, s[74:75]
	v_add_u32_e32 v215, s18, v185
	v_readfirstlane_b32 s18, v190
	s_mov_b32 m0, s18
	s_nop 0
	global_load_lds_dwordx4 v215, s[74:75]
	s_waitcnt vmcnt(8)
	s_waitcnt lgkmcnt(0)
	s_barrier
	v_mfma_f32_16x16x32_bf16 v[62:65], v[122:125], v[146:149], v[62:65]
	v_mfma_f32_16x16x32_bf16 v[46:49], v[122:125], v[154:157], v[46:49]
	v_mfma_f32_16x16x32_bf16 v[30:33], v[122:125], v[162:165], v[30:33]
	v_mfma_f32_16x16x32_bf16 v[14:17], v[122:125], v[170:173], v[14:17]
	v_mfma_f32_16x16x32_bf16 v[62:65], v[134:137], v[150:153], v[62:65]
	v_mfma_f32_16x16x32_bf16 v[46:49], v[134:137], v[158:161], v[46:49]
	v_mfma_f32_16x16x32_bf16 v[30:33], v[134:137], v[166:169], v[30:33]
	v_mfma_f32_16x16x32_bf16 v[14:17], v[134:137], v[174:177], v[14:17]
	s_barrier
	v_or_b32_e32 v122, 0x18000, v200
	v_add_u32_e32 v134, 0x18400, v200
	v_add_u32_e32 v138, 0x18800, v200
	v_add_u32_e32 v142, 0x18c00, v200
	ds_read_b128 v[122:125], v122
	ds_read_b128 v[134:137], v134
	ds_read_b128 v[138:141], v138
	ds_read_b128 v[142:145], v142
	s_lshl_b32 s5, s5, 12
	s_lshl_b32 s6, s6, 7
	s_add_i32 s5, s6, s5
	s_add_i32 s5, s5, 0x80000
	v_readfirstlane_b32 s6, v191
	v_add_u32_e32 v180, s5, v184
	s_mov_b32 m0, s6
	ds_read_b128 v[146:149], v199 offset:32768
	ds_read_b128 v[150:153], v199 offset:33792
	ds_read_b128 v[154:157], v199 offset:34816
	ds_read_b128 v[158:161], v199 offset:35840
	ds_read_b128 v[162:165], v199 offset:36864
	ds_read_b128 v[166:169], v199 offset:37888
	ds_read_b128 v[170:173], v199 offset:38912
	ds_read_b128 v[174:177], v199 offset:39936
	global_load_lds_dwordx4 v180, s[80:81]
	v_add_u32_e32 v180, s5, v185
	v_readfirstlane_b32 s5, v192
	s_mov_b32 m0, s5
	s_nop 0
	global_load_lds_dwordx4 v180, s[80:81]
	s_waitcnt lgkmcnt(8)
	v_or_b32_e32 v180, 0x1c000, v200
	v_add_u32_e32 v202, 0x1c400, v200
	v_add_u32_e32 v206, 0x1c800, v200
	v_add_u32_e32 v210, 0x1cc00, v200
	ds_read_b128 v[180:183], v180
	ds_read_b128 v[202:205], v202
	ds_read_b128 v[206:209], v206
	ds_read_b128 v[210:213], v210
	s_waitcnt vmcnt(8)
	s_waitcnt lgkmcnt(0)
	s_barrier
	v_mfma_f32_16x16x32_bf16 v[130:133], v[122:125], v[146:149], v[130:133]
	v_mfma_f32_16x16x32_bf16 v[110:113], v[122:125], v[154:157], v[110:113]
	v_mfma_f32_16x16x32_bf16 v[94:97], v[122:125], v[162:165], v[94:97]
	v_mfma_f32_16x16x32_bf16 v[78:81], v[122:125], v[170:173], v[78:81]
	v_mfma_f32_16x16x32_bf16 v[130:133], v[134:137], v[150:153], v[130:133]
	v_mfma_f32_16x16x32_bf16 v[110:113], v[134:137], v[158:161], v[110:113]
	v_mfma_f32_16x16x32_bf16 v[94:97], v[134:137], v[166:169], v[94:97]
	v_mfma_f32_16x16x32_bf16 v[78:81], v[134:137], v[174:177], v[78:81]
	s_barrier
	s_or_b32 s5, s7, 64
	s_or_b32 s3, s5, s3
	s_lshl_b32 s3, s3, 1
	v_readfirstlane_b32 s6, v193
	v_add_u32_e32 v214, s3, v184
	s_mov_b32 m0, s6
	global_load_lds_dwordx4 v214, s[74:75]
	v_add_u32_e32 v214, s3, v185
	v_readfirstlane_b32 s3, v194
	s_mov_b32 m0, s3
	s_nop 0
	global_load_lds_dwordx4 v214, s[74:75]
	s_or_b32 s3, s5, s10
	s_lshl_b32 s3, s3, 1
	v_readfirstlane_b32 s6, v195
	v_add_u32_e32 v214, s3, v184
	s_mov_b32 m0, s6
	ds_read_b128 v[146:149], v199 offset:49152
	ds_read_b128 v[150:153], v199 offset:50176
	ds_read_b128 v[154:157], v199 offset:51200
	ds_read_b128 v[158:161], v199 offset:52224
	ds_read_b128 v[162:165], v199 offset:53248
	ds_read_b128 v[166:169], v199 offset:54272
	ds_read_b128 v[170:173], v199 offset:55296
	ds_read_b128 v[174:177], v199 offset:56320
	global_load_lds_dwordx4 v214, s[80:81]
	v_add_u32_e32 v214, s3, v185
	v_readfirstlane_b32 s3, v196
	s_mov_b32 m0, s3
	s_nop 0
	global_load_lds_dwordx4 v214, s[80:81]
	s_or_b32 s3, s11, s5
	s_lshl_b32 s3, s3, 1
	v_readfirstlane_b32 s5, v197
	v_add_u32_e32 v215, s3, v184
	s_mov_b32 m0, s5
	s_nop 0
	global_load_lds_dwordx4 v215, s[74:75]
	v_add_u32_e32 v215, s3, v185
	v_readfirstlane_b32 s3, v198
	s_mov_b32 m0, s3
	s_nop 0
	global_load_lds_dwordx4 v215, s[74:75]
	s_waitcnt vmcnt(8)
	s_waitcnt lgkmcnt(0)
	s_barrier
	v_mfma_f32_16x16x32_bf16 v[62:65], v[122:125], v[146:149], v[62:65]
	v_mfma_f32_16x16x32_bf16 v[46:49], v[122:125], v[154:157], v[46:49]
	v_mfma_f32_16x16x32_bf16 v[30:33], v[122:125], v[162:165], v[30:33]
	v_mfma_f32_16x16x32_bf16 v[14:17], v[122:125], v[170:173], v[14:17]
	v_mfma_f32_16x16x32_bf16 v[62:65], v[134:137], v[150:153], v[62:65]
	v_mfma_f32_16x16x32_bf16 v[46:49], v[134:137], v[158:161], v[46:49]
	v_mfma_f32_16x16x32_bf16 v[30:33], v[134:137], v[166:169], v[30:33]
	v_mfma_f32_16x16x32_bf16 v[14:17], v[134:137], v[174:177], v[14:17]
	s_add_i32 s0, s0, 2
	s_cmp_gt_u32 s1, 29
	v_add_u32_e32 v0, 0x100, v0
	s_barrier
	s_cbranch_scc0 .Lpj48_loop
	s_branch .Lpj48_done

.LBB0_414:
	v_or_b32_e32 v122, 0x10000, v200
	v_add_u32_e32 v134, 0x10400, v200
	v_add_u32_e32 v138, 0x10800, v200
	v_add_u32_e32 v142, 0x10c00, v200
	ds_read_b128 v[122:125], v122
	ds_read_b128 v[134:137], v134
	ds_read_b128 v[138:141], v138
	ds_read_b128 v[142:145], v142
	s_add_i32 s1, s0, -2
	s_cmp_lt_u32 s1, 30
	s_cselect_b32 s3, s4, s16
	s_cselect_b32 s5, s2, s15
	v_add_u32_e32 v181, 0xc000, v179
	v_add_u32_e32 v180, 0xfffc0000, v0
	v_readfirstlane_b32 s6, v181
	s_mov_b32 m0, s6
	ds_read_b128 v[146:149], v199
	ds_read_b128 v[150:153], v199 offset:1024
	ds_read_b128 v[154:157], v199 offset:2048
	ds_read_b128 v[158:161], v199 offset:3072
	ds_read_b128 v[162:165], v199 offset:4096
	ds_read_b128 v[166:169], v199 offset:5120
	ds_read_b128 v[170:173], v199 offset:6144
	ds_read_b128 v[174:177], v199 offset:7168
	global_load_lds_dwordx4 v180, s[80:81]
	v_add_u32_e32 v180, 0xe000, v179
	s_nop 0
	v_readfirstlane_b32 s6, v180
	s_mov_b32 m0, s6
	s_nop 0
	global_load_lds_dwordx4 v0, s[80:81]
	s_waitcnt lgkmcnt(8)
	v_or_b32_e32 v180, 0x14000, v200
	v_add_u32_e32 v202, 0x14400, v200
	v_add_u32_e32 v206, 0x14800, v200
	v_add_u32_e32 v210, 0x14c00, v200
	ds_read_b128 v[180:183], v180
	ds_read_b128 v[202:205], v202
	ds_read_b128 v[206:209], v206
	ds_read_b128 v[210:213], v210
	s_waitcnt vmcnt(8)
	s_waitcnt lgkmcnt(0)
	s_barrier
	v_mfma_f32_16x16x32_bf16 v[130:133], v[122:125], v[146:149], v[130:133]
	v_mfma_f32_16x16x32_bf16 v[126:129], v[138:141], v[146:149], v[126:129]
	v_mfma_f32_16x16x32_bf16 v[110:113], v[122:125], v[154:157], v[110:113]
	v_mfma_f32_16x16x32_bf16 v[106:109], v[138:141], v[154:157], v[106:109]
	v_mfma_f32_16x16x32_bf16 v[94:97], v[122:125], v[162:165], v[94:97]
	v_mfma_f32_16x16x32_bf16 v[90:93], v[138:141], v[162:165], v[90:93]
	v_mfma_f32_16x16x32_bf16 v[78:81], v[122:125], v[170:173], v[78:81]
	v_mfma_f32_16x16x32_bf16 v[74:77], v[138:141], v[170:173], v[74:77]
	v_mfma_f32_16x16x32_bf16 v[130:133], v[134:137], v[150:153], v[130:133]
	v_mfma_f32_16x16x32_bf16 v[126:129], v[142:145], v[150:153], v[126:129]
	v_mfma_f32_16x16x32_bf16 v[110:113], v[134:137], v[158:161], v[110:113]
	v_mfma_f32_16x16x32_bf16 v[106:109], v[142:145], v[158:161], v[106:109]
	v_mfma_f32_16x16x32_bf16 v[94:97], v[134:137], v[166:169], v[94:97]
	v_mfma_f32_16x16x32_bf16 v[90:93], v[142:145], v[166:169], v[90:93]
	v_mfma_f32_16x16x32_bf16 v[78:81], v[134:137], v[174:177], v[78:81]
	v_mfma_f32_16x16x32_bf16 v[74:77], v[142:145], v[174:177], v[74:77]
	v_mfma_f32_16x16x32_bf16 v[118:121], v[180:183], v[146:149], v[118:121]
	v_mfma_f32_16x16x32_bf16 v[114:117], v[206:209], v[146:149], v[114:117]
	v_mfma_f32_16x16x32_bf16 v[102:105], v[180:183], v[154:157], v[102:105]
	v_mfma_f32_16x16x32_bf16 v[98:101], v[206:209], v[154:157], v[98:101]
	v_mfma_f32_16x16x32_bf16 v[86:89], v[180:183], v[162:165], v[86:89]
	v_mfma_f32_16x16x32_bf16 v[82:85], v[206:209], v[162:165], v[82:85]
	v_mfma_f32_16x16x32_bf16 v[70:73], v[180:183], v[170:173], v[70:73]
	v_mfma_f32_16x16x32_bf16 v[66:69], v[206:209], v[170:173], v[66:69]
	v_mfma_f32_16x16x32_bf16 v[118:121], v[202:205], v[150:153], v[118:121]
	v_mfma_f32_16x16x32_bf16 v[114:117], v[210:213], v[150:153], v[114:117]
	v_mfma_f32_16x16x32_bf16 v[102:105], v[202:205], v[158:161], v[102:105]
	v_mfma_f32_16x16x32_bf16 v[98:101], v[210:213], v[158:161], v[98:101]
	v_mfma_f32_16x16x32_bf16 v[86:89], v[202:205], v[166:169], v[86:89]
	v_mfma_f32_16x16x32_bf16 v[82:85], v[210:213], v[166:169], v[82:85]
	v_mfma_f32_16x16x32_bf16 v[70:73], v[202:205], v[174:177], v[70:73]
	v_mfma_f32_16x16x32_bf16 v[66:69], v[210:213], v[174:177], v[66:69]
	s_barrier
	s_cselect_b32 s6, s0, 0
	s_lshl_b32 s3, s3, 11
	s_lshl_b32 s7, s6, 6
	s_or_b32 s10, s3, s7
	s_lshl_b32 s10, s10, 1
	v_readfirstlane_b32 s11, v186
	v_add_u32_e32 v214, s10, v184
	s_mov_b32 m0, s11
	global_load_lds_dwordx4 v214, s[74:75]
	v_add_u32_e32 v214, s10, v185
	v_readfirstlane_b32 s10, v187
	s_mov_b32 m0, s10
	s_nop 0
	global_load_lds_dwordx4 v214, s[74:75]
	s_lshl_b32 s10, s5, 11
	s_or_b32 s11, s10, s7
	s_lshl_b32 s11, s11, 1
	v_readfirstlane_b32 s18, v179
	v_add_u32_e32 v214, s11, v184
	s_mov_b32 m0, s18
	ds_read_b128 v[146:149], v199 offset:16384
	ds_read_b128 v[150:153], v199 offset:17408
	ds_read_b128 v[154:157], v199 offset:18432
	ds_read_b128 v[158:161], v199 offset:19456
	ds_read_b128 v[162:165], v199 offset:20480
	ds_read_b128 v[166:169], v199 offset:21504
	ds_read_b128 v[170:173], v199 offset:22528
	ds_read_b128 v[174:177], v199 offset:23552
	global_load_lds_dwordx4 v214, s[80:81]
	v_add_u32_e32 v214, s11, v185
	v_readfirstlane_b32 s11, v188
	s_mov_b32 m0, s11
	s_nop 0
	global_load_lds_dwordx4 v214, s[80:81]
	s_or_b32 s11, s3, 0x40000
	s_or_b32 s18, s11, s7
	s_lshl_b32 s18, s18, 1
	v_readfirstlane_b32 s19, v189
	v_add_u32_e32 v215, s18, v184
	s_mov_b32 m0, s19
	s_nop 0
	global_load_lds_dwordx4 v215, s[74:75]
	v_add_u32_e32 v215, s18, v185
	v_readfirstlane_b32 s18, v190
	s_mov_b32 m0, s18
	s_nop 0
	global_load_lds_dwordx4 v215, s[74:75]
	s_waitcnt vmcnt(8)
	s_waitcnt lgkmcnt(0)
	s_barrier
	v_mfma_f32_16x16x32_bf16 v[62:65], v[122:125], v[146:149], v[62:65]
	v_mfma_f32_16x16x32_bf16 v[58:61], v[138:141], v[146:149], v[58:61]
	v_mfma_f32_16x16x32_bf16 v[46:49], v[122:125], v[154:157], v[46:49]
	v_mfma_f32_16x16x32_bf16 v[42:45], v[138:141], v[154:157], v[42:45]
	v_mfma_f32_16x16x32_bf16 v[30:33], v[122:125], v[162:165], v[30:33]
	v_mfma_f32_16x16x32_bf16 v[26:29], v[138:141], v[162:165], v[26:29]
	v_mfma_f32_16x16x32_bf16 v[14:17], v[122:125], v[170:173], v[14:17]
	v_mfma_f32_16x16x32_bf16 v[10:13], v[138:141], v[170:173], v[10:13]
	v_mfma_f32_16x16x32_bf16 v[62:65], v[134:137], v[150:153], v[62:65]
	v_mfma_f32_16x16x32_bf16 v[58:61], v[142:145], v[150:153], v[58:61]
	v_mfma_f32_16x16x32_bf16 v[46:49], v[134:137], v[158:161], v[46:49]
	v_mfma_f32_16x16x32_bf16 v[42:45], v[142:145], v[158:161], v[42:45]
	v_mfma_f32_16x16x32_bf16 v[30:33], v[134:137], v[166:169], v[30:33]
	v_mfma_f32_16x16x32_bf16 v[26:29], v[142:145], v[166:169], v[26:29]
	v_mfma_f32_16x16x32_bf16 v[14:17], v[134:137], v[174:177], v[14:17]
	v_mfma_f32_16x16x32_bf16 v[10:13], v[142:145], v[174:177], v[10:13]
	v_mfma_f32_16x16x32_bf16 v[54:57], v[180:183], v[146:149], v[54:57]
	v_mfma_f32_16x16x32_bf16 v[50:53], v[206:209], v[146:149], v[50:53]
	v_mfma_f32_16x16x32_bf16 v[38:41], v[180:183], v[154:157], v[38:41]
	v_mfma_f32_16x16x32_bf16 v[34:37], v[206:209], v[154:157], v[34:37]
	v_mfma_f32_16x16x32_bf16 v[22:25], v[180:183], v[162:165], v[22:25]
	v_mfma_f32_16x16x32_bf16 v[18:21], v[206:209], v[162:165], v[18:21]
	v_mfma_f32_16x16x32_bf16 v[6:9], v[180:183], v[170:173], v[6:9]
	v_mfma_f32_16x16x32_bf16 v[2:5], v[206:209], v[170:173], v[2:5]
	v_mfma_f32_16x16x32_bf16 v[54:57], v[202:205], v[150:153], v[54:57]
	v_mfma_f32_16x16x32_bf16 v[50:53], v[210:213], v[150:153], v[50:53]
	v_mfma_f32_16x16x32_bf16 v[38:41], v[202:205], v[158:161], v[38:41]
	v_mfma_f32_16x16x32_bf16 v[34:37], v[210:213], v[158:161], v[34:37]
	v_mfma_f32_16x16x32_bf16 v[22:25], v[202:205], v[166:169], v[22:25]
	v_mfma_f32_16x16x32_bf16 v[18:21], v[210:213], v[166:169], v[18:21]
	v_mfma_f32_16x16x32_bf16 v[6:9], v[202:205], v[174:177], v[6:9]
	v_mfma_f32_16x16x32_bf16 v[2:5], v[210:213], v[174:177], v[2:5]
	s_barrier
	v_or_b32_e32 v122, 0x18000, v200
	v_add_u32_e32 v134, 0x18400, v200
	v_add_u32_e32 v138, 0x18800, v200
	v_add_u32_e32 v142, 0x18c00, v200
	ds_read_b128 v[122:125], v122
	ds_read_b128 v[134:137], v134
	ds_read_b128 v[138:141], v138
	ds_read_b128 v[142:145], v142
	s_lshl_b32 s5, s5, 12
	s_lshl_b32 s6, s6, 7
	s_add_i32 s5, s6, s5
	s_add_i32 s5, s5, 0x80000
	v_readfirstlane_b32 s6, v191
	v_add_u32_e32 v180, s5, v184
	s_mov_b32 m0, s6
	ds_read_b128 v[146:149], v199 offset:32768
	ds_read_b128 v[150:153], v199 offset:33792
	ds_read_b128 v[154:157], v199 offset:34816
	ds_read_b128 v[158:161], v199 offset:35840
	ds_read_b128 v[162:165], v199 offset:36864
	ds_read_b128 v[166:169], v199 offset:37888
	ds_read_b128 v[170:173], v199 offset:38912
	ds_read_b128 v[174:177], v199 offset:39936
	global_load_lds_dwordx4 v180, s[80:81]
	v_add_u32_e32 v180, s5, v185
	v_readfirstlane_b32 s5, v192
	s_mov_b32 m0, s5
	s_nop 0
	global_load_lds_dwordx4 v180, s[80:81]
	s_waitcnt lgkmcnt(8)
	v_or_b32_e32 v180, 0x1c000, v200
	v_add_u32_e32 v202, 0x1c400, v200
	v_add_u32_e32 v206, 0x1c800, v200
	v_add_u32_e32 v210, 0x1cc00, v200
	ds_read_b128 v[180:183], v180
	ds_read_b128 v[202:205], v202
	ds_read_b128 v[206:209], v206
	ds_read_b128 v[210:213], v210
	s_waitcnt vmcnt(8)
	s_waitcnt lgkmcnt(0)
	s_barrier
	v_mfma_f32_16x16x32_bf16 v[130:133], v[122:125], v[146:149], v[130:133]
	v_mfma_f32_16x16x32_bf16 v[126:129], v[138:141], v[146:149], v[126:129]
	v_mfma_f32_16x16x32_bf16 v[110:113], v[122:125], v[154:157], v[110:113]
	v_mfma_f32_16x16x32_bf16 v[106:109], v[138:141], v[154:157], v[106:109]
	v_mfma_f32_16x16x32_bf16 v[94:97], v[122:125], v[162:165], v[94:97]
	v_mfma_f32_16x16x32_bf16 v[90:93], v[138:141], v[162:165], v[90:93]
	v_mfma_f32_16x16x32_bf16 v[78:81], v[122:125], v[170:173], v[78:81]
	v_mfma_f32_16x16x32_bf16 v[74:77], v[138:141], v[170:173], v[74:77]
	v_mfma_f32_16x16x32_bf16 v[130:133], v[134:137], v[150:153], v[130:133]
	v_mfma_f32_16x16x32_bf16 v[126:129], v[142:145], v[150:153], v[126:129]
	v_mfma_f32_16x16x32_bf16 v[110:113], v[134:137], v[158:161], v[110:113]
	v_mfma_f32_16x16x32_bf16 v[106:109], v[142:145], v[158:161], v[106:109]
	v_mfma_f32_16x16x32_bf16 v[94:97], v[134:137], v[166:169], v[94:97]
	v_mfma_f32_16x16x32_bf16 v[90:93], v[142:145], v[166:169], v[90:93]
	v_mfma_f32_16x16x32_bf16 v[78:81], v[134:137], v[174:177], v[78:81]
	v_mfma_f32_16x16x32_bf16 v[74:77], v[142:145], v[174:177], v[74:77]
	v_mfma_f32_16x16x32_bf16 v[118:121], v[180:183], v[146:149], v[118:121]
	v_mfma_f32_16x16x32_bf16 v[114:117], v[206:209], v[146:149], v[114:117]
	v_mfma_f32_16x16x32_bf16 v[102:105], v[180:183], v[154:157], v[102:105]
	v_mfma_f32_16x16x32_bf16 v[98:101], v[206:209], v[154:157], v[98:101]
	v_mfma_f32_16x16x32_bf16 v[86:89], v[180:183], v[162:165], v[86:89]
	v_mfma_f32_16x16x32_bf16 v[82:85], v[206:209], v[162:165], v[82:85]
	v_mfma_f32_16x16x32_bf16 v[70:73], v[180:183], v[170:173], v[70:73]
	v_mfma_f32_16x16x32_bf16 v[66:69], v[206:209], v[170:173], v[66:69]
	v_mfma_f32_16x16x32_bf16 v[118:121], v[202:205], v[150:153], v[118:121]
	v_mfma_f32_16x16x32_bf16 v[114:117], v[210:213], v[150:153], v[114:117]
	v_mfma_f32_16x16x32_bf16 v[102:105], v[202:205], v[158:161], v[102:105]
	v_mfma_f32_16x16x32_bf16 v[98:101], v[210:213], v[158:161], v[98:101]
	v_mfma_f32_16x16x32_bf16 v[86:89], v[202:205], v[166:169], v[86:89]
	v_mfma_f32_16x16x32_bf16 v[82:85], v[210:213], v[166:169], v[82:85]
	v_mfma_f32_16x16x32_bf16 v[70:73], v[202:205], v[174:177], v[70:73]
	v_mfma_f32_16x16x32_bf16 v[66:69], v[210:213], v[174:177], v[66:69]
	s_barrier
	s_or_b32 s5, s7, 64
	s_or_b32 s3, s5, s3
	s_lshl_b32 s3, s3, 1
	v_readfirstlane_b32 s6, v193
	v_add_u32_e32 v214, s3, v184
	s_mov_b32 m0, s6
	global_load_lds_dwordx4 v214, s[74:75]
	v_add_u32_e32 v214, s3, v185
	v_readfirstlane_b32 s3, v194
	s_mov_b32 m0, s3
	s_nop 0
	global_load_lds_dwordx4 v214, s[74:75]
	s_or_b32 s3, s5, s10
	s_lshl_b32 s3, s3, 1
	v_readfirstlane_b32 s6, v195
	v_add_u32_e32 v214, s3, v184
	s_mov_b32 m0, s6
	ds_read_b128 v[146:149], v199 offset:49152
	ds_read_b128 v[150:153], v199 offset:50176
	ds_read_b128 v[154:157], v199 offset:51200
	ds_read_b128 v[158:161], v199 offset:52224
	ds_read_b128 v[162:165], v199 offset:53248
	ds_read_b128 v[166:169], v199 offset:54272
	ds_read_b128 v[170:173], v199 offset:55296
	ds_read_b128 v[174:177], v199 offset:56320
	global_load_lds_dwordx4 v214, s[80:81]
	v_add_u32_e32 v214, s3, v185
	v_readfirstlane_b32 s3, v196
	s_mov_b32 m0, s3
	s_nop 0
	global_load_lds_dwordx4 v214, s[80:81]
	s_or_b32 s3, s11, s5
	s_lshl_b32 s3, s3, 1
	v_readfirstlane_b32 s5, v197
	v_add_u32_e32 v215, s3, v184
	s_mov_b32 m0, s5
	s_nop 0
	global_load_lds_dwordx4 v215, s[74:75]
	v_add_u32_e32 v215, s3, v185
	v_readfirstlane_b32 s3, v198
	s_mov_b32 m0, s3
	s_nop 0
	global_load_lds_dwordx4 v215, s[74:75]
	s_waitcnt vmcnt(8)
	s_waitcnt lgkmcnt(0)
	s_barrier
	v_mfma_f32_16x16x32_bf16 v[62:65], v[122:125], v[146:149], v[62:65]
	v_mfma_f32_16x16x32_bf16 v[58:61], v[138:141], v[146:149], v[58:61]
	v_mfma_f32_16x16x32_bf16 v[46:49], v[122:125], v[154:157], v[46:49]
	v_mfma_f32_16x16x32_bf16 v[42:45], v[138:141], v[154:157], v[42:45]
	v_mfma_f32_16x16x32_bf16 v[30:33], v[122:125], v[162:165], v[30:33]
	v_mfma_f32_16x16x32_bf16 v[26:29], v[138:141], v[162:165], v[26:29]
	v_mfma_f32_16x16x32_bf16 v[14:17], v[122:125], v[170:173], v[14:17]
	v_mfma_f32_16x16x32_bf16 v[10:13], v[138:141], v[170:173], v[10:13]
	v_mfma_f32_16x16x32_bf16 v[62:65], v[134:137], v[150:153], v[62:65]
	v_mfma_f32_16x16x32_bf16 v[58:61], v[142:145], v[150:153], v[58:61]
	v_mfma_f32_16x16x32_bf16 v[46:49], v[134:137], v[158:161], v[46:49]
	v_mfma_f32_16x16x32_bf16 v[42:45], v[142:145], v[158:161], v[42:45]
	v_mfma_f32_16x16x32_bf16 v[30:33], v[134:137], v[166:169], v[30:33]
	v_mfma_f32_16x16x32_bf16 v[26:29], v[142:145], v[166:169], v[26:29]
	v_mfma_f32_16x16x32_bf16 v[14:17], v[134:137], v[174:177], v[14:17]
	v_mfma_f32_16x16x32_bf16 v[10:13], v[142:145], v[174:177], v[10:13]
	v_mfma_f32_16x16x32_bf16 v[54:57], v[180:183], v[146:149], v[54:57]
	v_mfma_f32_16x16x32_bf16 v[50:53], v[206:209], v[146:149], v[50:53]
	v_mfma_f32_16x16x32_bf16 v[38:41], v[180:183], v[154:157], v[38:41]
	v_mfma_f32_16x16x32_bf16 v[34:37], v[206:209], v[154:157], v[34:37]
	v_mfma_f32_16x16x32_bf16 v[22:25], v[180:183], v[162:165], v[22:25]
	v_mfma_f32_16x16x32_bf16 v[18:21], v[206:209], v[162:165], v[18:21]
	v_mfma_f32_16x16x32_bf16 v[6:9], v[180:183], v[170:173], v[6:9]
	v_mfma_f32_16x16x32_bf16 v[2:5], v[206:209], v[170:173], v[2:5]
	v_mfma_f32_16x16x32_bf16 v[54:57], v[202:205], v[150:153], v[54:57]
	v_mfma_f32_16x16x32_bf16 v[50:53], v[210:213], v[150:153], v[50:53]
	v_mfma_f32_16x16x32_bf16 v[38:41], v[202:205], v[158:161], v[38:41]
	v_mfma_f32_16x16x32_bf16 v[34:37], v[210:213], v[158:161], v[34:37]
	v_mfma_f32_16x16x32_bf16 v[22:25], v[202:205], v[166:169], v[22:25]
	v_mfma_f32_16x16x32_bf16 v[18:21], v[210:213], v[166:169], v[18:21]
	v_mfma_f32_16x16x32_bf16 v[6:9], v[202:205], v[174:177], v[6:9]
	v_mfma_f32_16x16x32_bf16 v[2:5], v[210:213], v[174:177], v[2:5]
	s_add_i32 s0, s0, 2
	s_cmp_gt_u32 s1, 29
	v_add_u32_e32 v0, 0x100, v0
	s_barrier
	s_cbranch_scc0 .LBB0_414
